# v98 with the G1 epilogue stores as system-scope non-temporal (sc0 sc1 nt: written through, not retained)
# baseline (speedup 1.0000x reference)
; #define LAS __attribute__((address_space(3)))
; #define GAS __attribute__((address_space(1)))
; __host__ __device__ __forceinline__ size_t bl512(size_t row, int col) { return ((row >> 5) * 64 + (size_t)(col >> 3)) * 256 + (row & 31) * 8 + (col & 7); }
;     __device__ __forceinline__ void operator()(const f32x4 (&acc)[2][2][4][2], const Unit& u, int wr, int wc, int fr, int fq) const {
;     ...
;         const int slot = (tags[0] == u.pm) ? 0 : (tags[1] == u.pm) ? 1 : -1;
;         const LAS float* rtab = (const LAS float*)rsc + (slot > 0 ? 256 : 0) + wr * 64 + fr;
; #pragma unroll
;         for (int ai = 0; ai < 2; ++ai)
; #pragma unroll
;             for (int m = 0; m < 4; ++m) {
;                 const int row = row0 + ai * HALF + m * 16;
;                 float rs;
;                 if (slot >= 0) rs = rtab[ai * HALF + m * 16];
;                 else {
;                     const f32x4 pv = *(const GAS f32x4*)(part + (size_t)row * 16 + fq * 4);
;                     float s = (pv[0] + pv[1]) + (pv[2] + pv[3]);
;                     s = row4_sum(s);
;                     rs = __builtin_amdgcn_rsqf(s * (1.0f / DM) + RMS_EPS);
;                 }
;                 f32x4 v[2][2];
; #pragma unroll
;                 for (int bj = 0; bj < 2; ++bj)
; #pragma unroll
;                     for (int n = 0; n < 2; ++n) v[bj][n] = acc[ai][bj][m][n] * rs;
;     ...
;                 GAS f16* rowp = isqg ? QG + (size_t)dsec * QG_SEC + bl512((size_t)row, cs) : KV + (size_t)row * KVW + dsec * 512 + cs;
; #pragma unroll
;                 for (int bj = 0; bj < 2; ++bj) {
;                     u32x4 w; w.x = pkh(v[bj][0][0], v[bj][0][1]); w.y = pkh(v[bj][0][2], v[bj][0][3]); w.z = pkh(v[bj][1][0], v[bj][1][1]); w.w = pkh(v[bj][1][2], v[bj][1][3]);
;                     *(GAS u32x4*)(rowp + bjstep * bj) = w;
;                 }
.Lepi_kvp:
	s_and_b32 s0, s70, 1
	s_lshl_b32 s0, s0, 10
	v_add_u32_e32 v132, s0, v219
	ds_read_b32 v134, v132
	ds_read_b32 v136, v132 offset:64
	ds_read_b32 v138, v132 offset:128
	ds_read_b32 v140, v132 offset:192
	ds_read_b32 v142, v132 offset:512
	ds_read_b32 v144, v132 offset:576
	ds_read_b32 v146, v132 offset:640
	ds_read_b32 v148, v132 offset:704
	s_lshr_b32 s0, s69, 2
	s_and_b32 s1, s69, 1
	v_lshl_add_u32 v133, s68, 8, v187
	v_lshlrev_b32_e32 v133, 12, v133
	v_lshl_add_u32 v133, v220, 1, v133
	s_lshl_b32 s0, s0, 10
	s_lshl_b32 s1, s1, 9
	s_add_u32 s0, s0, s1
	s_add_u32 s4, s8, s0
	s_addc_u32 s5, s9, 0
	s_waitcnt lgkmcnt(0)
	s_mov_b32 s6, s4
	s_mov_b32 s7, s5
	v_pk_mul_f32 v[128:129], v[128:129], v[134:135] op_sel_hi:[1,0]
	v_pk_mul_f32 v[130:131], v[130:131], v[134:135] op_sel_hi:[1,0]
	v_pk_mul_f32 v[124:125], v[124:125], v[134:135] op_sel_hi:[1,0]
	v_pk_mul_f32 v[126:127], v[126:127], v[134:135] op_sel_hi:[1,0]
	v_pk_mul_f32 v[96:97], v[96:97], v[134:135] op_sel_hi:[1,0]
	v_pk_mul_f32 v[98:99], v[98:99], v[134:135] op_sel_hi:[1,0]
	v_pk_mul_f32 v[92:93], v[92:93], v[134:135] op_sel_hi:[1,0]
	v_pk_mul_f32 v[94:95], v[94:95], v[134:135] op_sel_hi:[1,0]
	v_cvt_pk_f16_f32 v152, v128, v129
	v_cvt_pk_f16_f32 v153, v130, v131
	v_cvt_pk_f16_f32 v154, v124, v125
	v_cvt_pk_f16_f32 v155, v126, v127
	global_store_dwordx4 v133, v[152:155], s[6:7] sc0 sc1 nt
	v_cvt_pk_f16_f32 v156, v96, v97
	v_cvt_pk_f16_f32 v157, v98, v99
	v_cvt_pk_f16_f32 v158, v92, v93
	v_cvt_pk_f16_f32 v159, v94, v95
	global_store_dwordx4 v133, v[156:159], s[6:7] offset:64 sc0 sc1 nt
	s_add_u32 s6, s4, 0x10000
	s_addc_u32 s7, s5, 0
	v_pk_mul_f32 v[120:121], v[120:121], v[136:137] op_sel_hi:[1,0]
	v_pk_mul_f32 v[122:123], v[122:123], v[136:137] op_sel_hi:[1,0]
	v_pk_mul_f32 v[116:117], v[116:117], v[136:137] op_sel_hi:[1,0]
	v_pk_mul_f32 v[118:119], v[118:119], v[136:137] op_sel_hi:[1,0]
	v_pk_mul_f32 v[88:89], v[88:89], v[136:137] op_sel_hi:[1,0]
	v_pk_mul_f32 v[90:91], v[90:91], v[136:137] op_sel_hi:[1,0]
	v_pk_mul_f32 v[84:85], v[84:85], v[136:137] op_sel_hi:[1,0]
	v_pk_mul_f32 v[86:87], v[86:87], v[136:137] op_sel_hi:[1,0]
	v_cvt_pk_f16_f32 v160, v120, v121
	v_cvt_pk_f16_f32 v161, v122, v123
	v_cvt_pk_f16_f32 v162, v116, v117
	v_cvt_pk_f16_f32 v163, v118, v119
	global_store_dwordx4 v133, v[160:163], s[6:7] sc0 sc1 nt
	v_cvt_pk_f16_f32 v164, v88, v89
	v_cvt_pk_f16_f32 v165, v90, v91
	v_cvt_pk_f16_f32 v166, v84, v85
	v_cvt_pk_f16_f32 v167, v86, v87
	global_store_dwordx4 v133, v[164:167], s[6:7] offset:64 sc0 sc1 nt
	s_add_u32 s6, s4, 0x20000
	s_addc_u32 s7, s5, 0
	v_pk_mul_f32 v[112:113], v[112:113], v[138:139] op_sel_hi:[1,0]
	v_pk_mul_f32 v[114:115], v[114:115], v[138:139] op_sel_hi:[1,0]
	v_pk_mul_f32 v[108:109], v[108:109], v[138:139] op_sel_hi:[1,0]
	v_pk_mul_f32 v[110:111], v[110:111], v[138:139] op_sel_hi:[1,0]
	v_pk_mul_f32 v[80:81], v[80:81], v[138:139] op_sel_hi:[1,0]
	v_pk_mul_f32 v[82:83], v[82:83], v[138:139] op_sel_hi:[1,0]
	v_pk_mul_f32 v[76:77], v[76:77], v[138:139] op_sel_hi:[1,0]
	v_pk_mul_f32 v[78:79], v[78:79], v[138:139] op_sel_hi:[1,0]
	v_cvt_pk_f16_f32 v152, v112, v113
	v_cvt_pk_f16_f32 v153, v114, v115
	v_cvt_pk_f16_f32 v154, v108, v109
	v_cvt_pk_f16_f32 v155, v110, v111
	global_store_dwordx4 v133, v[152:155], s[6:7] sc0 sc1 nt
	v_cvt_pk_f16_f32 v156, v80, v81
	v_cvt_pk_f16_f32 v157, v82, v83
	v_cvt_pk_f16_f32 v158, v76, v77
	v_cvt_pk_f16_f32 v159, v78, v79
	global_store_dwordx4 v133, v[156:159], s[6:7] offset:64 sc0 sc1 nt
	s_add_u32 s6, s4, 0x30000
	s_addc_u32 s7, s5, 0
	v_pk_mul_f32 v[104:105], v[104:105], v[140:141] op_sel_hi:[1,0]
	v_pk_mul_f32 v[106:107], v[106:107], v[140:141] op_sel_hi:[1,0]
	v_pk_mul_f32 v[100:101], v[100:101], v[140:141] op_sel_hi:[1,0]
	v_pk_mul_f32 v[102:103], v[102:103], v[140:141] op_sel_hi:[1,0]
	v_pk_mul_f32 v[72:73], v[72:73], v[140:141] op_sel_hi:[1,0]
	v_pk_mul_f32 v[74:75], v[74:75], v[140:141] op_sel_hi:[1,0]
	v_pk_mul_f32 v[68:69], v[68:69], v[140:141] op_sel_hi:[1,0]
	v_pk_mul_f32 v[70:71], v[70:71], v[140:141] op_sel_hi:[1,0]
	v_cvt_pk_f16_f32 v160, v104, v105
	v_cvt_pk_f16_f32 v161, v106, v107
	v_cvt_pk_f16_f32 v162, v100, v101
	v_cvt_pk_f16_f32 v163, v102, v103
	global_store_dwordx4 v133, v[160:163], s[6:7] sc0 sc1 nt
	v_cvt_pk_f16_f32 v164, v72, v73
	v_cvt_pk_f16_f32 v165, v74, v75
	v_cvt_pk_f16_f32 v166, v68, v69
	v_cvt_pk_f16_f32 v167, v70, v71
	global_store_dwordx4 v133, v[164:167], s[6:7] offset:64 sc0 sc1 nt
	s_add_u32 s6, s4, 0x80000
	s_addc_u32 s7, s5, 0
	v_pk_mul_f32 v[64:65], v[64:65], v[142:143] op_sel_hi:[1,0]
	v_pk_mul_f32 v[66:67], v[66:67], v[142:143] op_sel_hi:[1,0]
	v_pk_mul_f32 v[60:61], v[60:61], v[142:143] op_sel_hi:[1,0]
	v_pk_mul_f32 v[62:63], v[62:63], v[142:143] op_sel_hi:[1,0]
	v_pk_mul_f32 v[32:33], v[32:33], v[142:143] op_sel_hi:[1,0]
	v_pk_mul_f32 v[34:35], v[34:35], v[142:143] op_sel_hi:[1,0]
	v_pk_mul_f32 v[28:29], v[28:29], v[142:143] op_sel_hi:[1,0]
	v_pk_mul_f32 v[30:31], v[30:31], v[142:143] op_sel_hi:[1,0]
	v_cvt_pk_f16_f32 v152, v64, v65
	v_cvt_pk_f16_f32 v153, v66, v67
	v_cvt_pk_f16_f32 v154, v60, v61
	v_cvt_pk_f16_f32 v155, v62, v63
	global_store_dwordx4 v133, v[152:155], s[6:7] sc0 sc1 nt
	v_cvt_pk_f16_f32 v156, v32, v33
	v_cvt_pk_f16_f32 v157, v34, v35
	v_cvt_pk_f16_f32 v158, v28, v29
	v_cvt_pk_f16_f32 v159, v30, v31
	global_store_dwordx4 v133, v[156:159], s[6:7] offset:64 sc0 sc1 nt
	s_add_u32 s6, s4, 0x90000
	s_addc_u32 s7, s5, 0
	v_pk_mul_f32 v[56:57], v[56:57], v[144:145] op_sel_hi:[1,0]
	v_pk_mul_f32 v[58:59], v[58:59], v[144:145] op_sel_hi:[1,0]
	v_pk_mul_f32 v[52:53], v[52:53], v[144:145] op_sel_hi:[1,0]
	v_pk_mul_f32 v[54:55], v[54:55], v[144:145] op_sel_hi:[1,0]
;     __device__ __forceinline__ void operator()(const f32x4 (&acc)[2][2][4][2], const Unit& u, int wr, int wc, int fr, int fq) const {
;     ...
;         const LAS int* tags = (const LAS int*)(rsc + 2048);
;         const int slot = (tags[0] == u.pm) ? 0 : (tags[1] == u.pm) ? 1 : -1;
;         const LAS float* rtab = (const LAS float*)rsc + (slot > 0 ? 256 : 0) + wr * 64 + fr;
; #pragma unroll
;         for (int ai = 0; ai < 2; ++ai)
; #pragma unroll
;             for (int m = 0; m < 4; ++m) {
;                 const int row = row0 + ai * HALF + m * 16;
;                 float rs;
;                 if (slot >= 0) rs = rtab[ai * HALF + m * 16];
;                 else {
;                     const f32x4 pv = *(const GAS f32x4*)(part + (size_t)row * 16 + fq * 4);
;                     float s = (pv[0] + pv[1]) + (pv[2] + pv[3]);
;                     s = row4_sum(s);
;                     rs = __builtin_amdgcn_rsqf(s * (1.0f / DM) + RMS_EPS);
;                 }
;                 f32x4 v[2][2];
; #pragma unroll
;                 for (int bj = 0; bj < 2; ++bj)
; #pragma unroll
;                     for (int n = 0; n < 2; ++n) v[bj][n] = acc[ai][bj][m][n] * rs;
;                 if (sec == 4 || sec == 5) {
;                     float ss = 0.f;
; #pragma unroll
;                     for (int bj = 0; bj < 2; ++bj)
; #pragma unroll
;                         for (int n = 0; n < 2; ++n) { const f32x4 x = v[bj][n]; ss += (x[0] * x[0] + x[1] * x[1]) + (x[2] * x[2] + x[3] * x[3]); }
;                     ss = row4_sum(ss);
;                     float rn = __builtin_amdgcn_rsqf(ss * (1.0f / 64.0f) + RMS_EPS);
;                     if (sec == 4) rn *= QS;
; #pragma unroll
;                     for (int bj = 0; bj < 2; ++bj)
; #pragma unroll
;                         for (int n = 0; n < 2; ++n) v[bj][n] = v[bj][n] * rn * gain[bj][n];
;                 } else if (sec == 0) {
; #pragma unroll
;                     for (int bj = 0; bj < 2; ++bj)
; #pragma unroll
;                         for (int n = 0; n < 2; ++n) v[bj][n] = v[bj][n] * QS;
;                 } else if (sec == 3 || sec == 7) {
; #pragma unroll
;                     for (int bj = 0; bj < 2; ++bj)
; #pragma unroll
;                         for (int n = 0; n < 2; ++n)
; #pragma unroll
;                             for (int e = 0; e < 4; ++e) v[bj][n][e] = silu_f(v[bj][n][e]);
;                 }
	v_pk_mul_f32 v[24:25], v[24:25], v[144:145] op_sel_hi:[1,0]
	v_pk_mul_f32 v[26:27], v[26:27], v[144:145] op_sel_hi:[1,0]
	v_pk_mul_f32 v[20:21], v[20:21], v[144:145] op_sel_hi:[1,0]
	v_pk_mul_f32 v[22:23], v[22:23], v[144:145] op_sel_hi:[1,0]
	v_cvt_pk_f16_f32 v160, v56, v57
	v_cvt_pk_f16_f32 v161, v58, v59
	v_cvt_pk_f16_f32 v162, v52, v53
	v_cvt_pk_f16_f32 v163, v54, v55
	global_store_dwordx4 v133, v[160:163], s[6:7] sc0 sc1 nt
	v_cvt_pk_f16_f32 v164, v24, v25
	v_cvt_pk_f16_f32 v165, v26, v27
	v_cvt_pk_f16_f32 v166, v20, v21
	v_cvt_pk_f16_f32 v167, v22, v23
	global_store_dwordx4 v133, v[164:167], s[6:7] offset:64 sc0 sc1 nt
	s_add_u32 s6, s4, 0xa0000
	s_addc_u32 s7, s5, 0
	v_pk_mul_f32 v[48:49], v[48:49], v[146:147] op_sel_hi:[1,0]
	v_pk_mul_f32 v[50:51], v[50:51], v[146:147] op_sel_hi:[1,0]
	v_pk_mul_f32 v[44:45], v[44:45], v[146:147] op_sel_hi:[1,0]
	v_pk_mul_f32 v[46:47], v[46:47], v[146:147] op_sel_hi:[1,0]
	v_pk_mul_f32 v[16:17], v[16:17], v[146:147] op_sel_hi:[1,0]
	v_pk_mul_f32 v[18:19], v[18:19], v[146:147] op_sel_hi:[1,0]
	v_pk_mul_f32 v[12:13], v[12:13], v[146:147] op_sel_hi:[1,0]
	v_pk_mul_f32 v[14:15], v[14:15], v[146:147] op_sel_hi:[1,0]
	v_cvt_pk_f16_f32 v152, v48, v49
	v_cvt_pk_f16_f32 v153, v50, v51
	v_cvt_pk_f16_f32 v154, v44, v45
	v_cvt_pk_f16_f32 v155, v46, v47
	global_store_dwordx4 v133, v[152:155], s[6:7] sc0 sc1 nt
	v_cvt_pk_f16_f32 v156, v16, v17
	v_cvt_pk_f16_f32 v157, v18, v19
	v_cvt_pk_f16_f32 v158, v12, v13
	v_cvt_pk_f16_f32 v159, v14, v15
	global_store_dwordx4 v133, v[156:159], s[6:7] offset:64 sc0 sc1 nt
	s_add_u32 s6, s4, 0xb0000
	s_addc_u32 s7, s5, 0
	v_pk_mul_f32 v[40:41], v[40:41], v[148:149] op_sel_hi:[1,0]
	v_pk_mul_f32 v[42:43], v[42:43], v[148:149] op_sel_hi:[1,0]
	v_pk_mul_f32 v[36:37], v[36:37], v[148:149] op_sel_hi:[1,0]
	v_pk_mul_f32 v[38:39], v[38:39], v[148:149] op_sel_hi:[1,0]
	v_pk_mul_f32 v[8:9], v[8:9], v[148:149] op_sel_hi:[1,0]
	v_pk_mul_f32 v[10:11], v[10:11], v[148:149] op_sel_hi:[1,0]
	v_pk_mul_f32 v[4:5], v[4:5], v[148:149] op_sel_hi:[1,0]
	v_pk_mul_f32 v[6:7], v[6:7], v[148:149] op_sel_hi:[1,0]
	v_cvt_pk_f16_f32 v160, v40, v41
	v_cvt_pk_f16_f32 v161, v42, v43
	v_cvt_pk_f16_f32 v162, v36, v37
	v_cvt_pk_f16_f32 v163, v38, v39
	global_store_dwordx4 v133, v[160:163], s[6:7] sc0 sc1 nt
	v_cvt_pk_f16_f32 v164, v8, v9
	v_cvt_pk_f16_f32 v165, v10, v11
	v_cvt_pk_f16_f32 v166, v4, v5
	v_cvt_pk_f16_f32 v167, v6, v7
	global_store_dwordx4 v133, v[164:167], s[6:7] offset:64 sc0 sc1 nt
	s_branch .Lepi_done_g1
.Lepi_qs:
	s_and_b32 s0, s70, 1
	s_lshl_b32 s0, s0, 10
	v_add_u32_e32 v132, s0, v219
	ds_read_b32 v134, v132
	ds_read_b32 v136, v132 offset:64
	ds_read_b32 v138, v132 offset:128
	ds_read_b32 v140, v132 offset:192
	ds_read_b32 v142, v132 offset:512
	ds_read_b32 v144, v132 offset:576
	ds_read_b32 v146, v132 offset:640
	ds_read_b32 v148, v132 offset:704
	s_lshr_b32 s0, s69, 2
	s_and_b32 s1, s69, 1
	v_lshrrev_b32_e32 v2, 6, v187
	v_lshrrev_b32_e32 v133, 3, v220
	v_lshl_add_u32 v133, v2, 7, v133
	v_and_b32_e32 v2, 15, v187
	v_lshlrev_b32_e32 v133, 8, v133
	v_lshl_add_u32 v133, v2, 3, v133
	v_lshlrev_b32_e32 v133, 1, v133
	s_lshl_b32 s0, s0, 25
	s_lshl_b32 s1, s1, 14
	s_add_u32 s0, s0, s1
	s_lshl_b32 s1, s68, 18
	s_add_u32 s0, s0, s1
	s_add_u32 s4, s82, s0
	s_addc_u32 s5, s83, 0
	s_waitcnt lgkmcnt(0)
	s_mov_b32 s6, s4
	s_mov_b32 s7, s5
	v_pk_mul_f32 v[128:129], v[128:129], v[134:135] op_sel_hi:[1,0]
	v_pk_mul_f32 v[130:131], v[130:131], v[134:135] op_sel_hi:[1,0]
	v_pk_mul_f32 v[124:125], v[124:125], v[134:135] op_sel_hi:[1,0]
	v_pk_mul_f32 v[126:127], v[126:127], v[134:135] op_sel_hi:[1,0]
	v_pk_mul_f32 v[96:97], v[96:97], v[134:135] op_sel_hi:[1,0]
	v_pk_mul_f32 v[98:99], v[98:99], v[134:135] op_sel_hi:[1,0]
	v_pk_mul_f32 v[92:93], v[92:93], v[134:135] op_sel_hi:[1,0]
	v_pk_mul_f32 v[94:95], v[94:95], v[134:135] op_sel_hi:[1,0]
	v_pk_mul_f32 v[128:129], v[128:129], s[78:79] op_sel_hi:[1,0]
	v_pk_mul_f32 v[130:131], v[130:131], s[78:79] op_sel_hi:[1,0]
	v_pk_mul_f32 v[124:125], v[124:125], s[78:79] op_sel_hi:[1,0]
	v_pk_mul_f32 v[126:127], v[126:127], s[78:79] op_sel_hi:[1,0]
	v_pk_mul_f32 v[96:97], v[96:97], s[78:79] op_sel_hi:[1,0]
	v_pk_mul_f32 v[98:99], v[98:99], s[78:79] op_sel_hi:[1,0]
	v_pk_mul_f32 v[92:93], v[92:93], s[78:79] op_sel_hi:[1,0]
	v_pk_mul_f32 v[94:95], v[94:95], s[78:79] op_sel_hi:[1,0]
	v_cvt_pk_f16_f32 v152, v128, v129
	v_cvt_pk_f16_f32 v153, v130, v131
	v_cvt_pk_f16_f32 v154, v124, v125
	v_cvt_pk_f16_f32 v155, v126, v127
	global_store_dwordx4 v133, v[152:155], s[6:7] sc0 sc1 nt
	v_cvt_pk_f16_f32 v156, v96, v97
	v_cvt_pk_f16_f32 v157, v98, v99
	v_cvt_pk_f16_f32 v158, v92, v93
	v_cvt_pk_f16_f32 v159, v94, v95
	global_store_dwordx4 v133, v[156:159], s[6:7] offset:2048 sc0 sc1 nt
	s_add_u32 s6, s4, 0x100
	s_addc_u32 s7, s5, 0
	v_pk_mul_f32 v[120:121], v[120:121], v[136:137] op_sel_hi:[1,0]
	v_pk_mul_f32 v[122:123], v[122:123], v[136:137] op_sel_hi:[1,0]
	v_pk_mul_f32 v[116:117], v[116:117], v[136:137] op_sel_hi:[1,0]
	v_pk_mul_f32 v[118:119], v[118:119], v[136:137] op_sel_hi:[1,0]
	v_pk_mul_f32 v[88:89], v[88:89], v[136:137] op_sel_hi:[1,0]
	v_pk_mul_f32 v[90:91], v[90:91], v[136:137] op_sel_hi:[1,0]
	v_pk_mul_f32 v[84:85], v[84:85], v[136:137] op_sel_hi:[1,0]
	v_pk_mul_f32 v[86:87], v[86:87], v[136:137] op_sel_hi:[1,0]
	v_pk_mul_f32 v[120:121], v[120:121], s[78:79] op_sel_hi:[1,0]
	v_pk_mul_f32 v[122:123], v[122:123], s[78:79] op_sel_hi:[1,0]
	v_pk_mul_f32 v[116:117], v[116:117], s[78:79] op_sel_hi:[1,0]
	v_pk_mul_f32 v[118:119], v[118:119], s[78:79] op_sel_hi:[1,0]
	v_pk_mul_f32 v[88:89], v[88:89], s[78:79] op_sel_hi:[1,0]
	v_pk_mul_f32 v[90:91], v[90:91], s[78:79] op_sel_hi:[1,0]
; #define GAS __attribute__((address_space(1)))
; __host__ __device__ __forceinline__ size_t bl512(size_t row, int col) { return ((row >> 5) * 64 + (size_t)(col >> 3)) * 256 + (row & 31) * 8 + (col & 7); }
; __device__ __forceinline__ float silu_f(float v) { return v * __builtin_amdgcn_rcpf(1.0f + __builtin_amdgcn_exp2f(-v * LOG2E)); }
;     __device__ __forceinline__ void operator()(const f32x4 (&acc)[2][2][4][2], const Unit& u, int wr, int wc, int fr, int fq) const {
;     ...
;                 f32x4 v[2][2];
; #pragma unroll
;                 for (int bj = 0; bj < 2; ++bj)
; #pragma unroll
;                     for (int n = 0; n < 2; ++n) v[bj][n] = acc[ai][bj][m][n] * rs;
;                 if (sec == 4 || sec == 5) {
;                     float ss = 0.f;
; #pragma unroll
;                     for (int bj = 0; bj < 2; ++bj)
; #pragma unroll
;                         for (int n = 0; n < 2; ++n) { const f32x4 x = v[bj][n]; ss += (x[0] * x[0] + x[1] * x[1]) + (x[2] * x[2] + x[3] * x[3]); }
;                     ss = row4_sum(ss);
;                     float rn = __builtin_amdgcn_rsqf(ss * (1.0f / 64.0f) + RMS_EPS);
;                     if (sec == 4) rn *= QS;
; #pragma unroll
;                     for (int bj = 0; bj < 2; ++bj)
; #pragma unroll
;                         for (int n = 0; n < 2; ++n) v[bj][n] = v[bj][n] * rn * gain[bj][n];
;                 } else if (sec == 0) {
; #pragma unroll
;                     for (int bj = 0; bj < 2; ++bj)
; #pragma unroll
;                         for (int n = 0; n < 2; ++n) v[bj][n] = v[bj][n] * QS;
;                 } else if (sec == 3 || sec == 7) {
; #pragma unroll
;                     for (int bj = 0; bj < 2; ++bj)
; #pragma unroll
;                         for (int n = 0; n < 2; ++n)
; #pragma unroll
;                             for (int e = 0; e < 4; ++e) v[bj][n][e] = silu_f(v[bj][n][e]);
;                 }
;                 GAS f16* rowp = isqg ? QG + (size_t)dsec * QG_SEC + bl512((size_t)row, cs) : KV + (size_t)row * KVW + dsec * 512 + cs;
; #pragma unroll
;                 for (int bj = 0; bj < 2; ++bj) {
;                     u32x4 w; w.x = pkh(v[bj][0][0], v[bj][0][1]); w.y = pkh(v[bj][0][2], v[bj][0][3]); w.z = pkh(v[bj][1][0], v[bj][1][1]); w.w = pkh(v[bj][1][2], v[bj][1][3]);
;                     *(GAS u32x4*)(rowp + bjstep * bj) = w;
;                 }
	v_pk_mul_f32 v[84:85], v[84:85], s[78:79] op_sel_hi:[1,0]
	v_pk_mul_f32 v[86:87], v[86:87], s[78:79] op_sel_hi:[1,0]
	v_cvt_pk_f16_f32 v160, v120, v121
	v_cvt_pk_f16_f32 v161, v122, v123
	v_cvt_pk_f16_f32 v162, v116, v117
	v_cvt_pk_f16_f32 v163, v118, v119
	global_store_dwordx4 v133, v[160:163], s[6:7] sc0 sc1 nt
	v_cvt_pk_f16_f32 v164, v88, v89
	v_cvt_pk_f16_f32 v165, v90, v91
	v_cvt_pk_f16_f32 v166, v84, v85
	v_cvt_pk_f16_f32 v167, v86, v87
	global_store_dwordx4 v133, v[164:167], s[6:7] offset:2048 sc0 sc1 nt
	s_add_u32 s6, s4, 0x8000
	s_addc_u32 s7, s5, 0
	v_pk_mul_f32 v[112:113], v[112:113], v[138:139] op_sel_hi:[1,0]
	v_pk_mul_f32 v[114:115], v[114:115], v[138:139] op_sel_hi:[1,0]
	v_pk_mul_f32 v[108:109], v[108:109], v[138:139] op_sel_hi:[1,0]
	v_pk_mul_f32 v[110:111], v[110:111], v[138:139] op_sel_hi:[1,0]
	v_pk_mul_f32 v[80:81], v[80:81], v[138:139] op_sel_hi:[1,0]
	v_pk_mul_f32 v[82:83], v[82:83], v[138:139] op_sel_hi:[1,0]
	v_pk_mul_f32 v[76:77], v[76:77], v[138:139] op_sel_hi:[1,0]
	v_pk_mul_f32 v[78:79], v[78:79], v[138:139] op_sel_hi:[1,0]
	v_pk_mul_f32 v[112:113], v[112:113], s[78:79] op_sel_hi:[1,0]
	v_pk_mul_f32 v[114:115], v[114:115], s[78:79] op_sel_hi:[1,0]
	v_pk_mul_f32 v[108:109], v[108:109], s[78:79] op_sel_hi:[1,0]
	v_pk_mul_f32 v[110:111], v[110:111], s[78:79] op_sel_hi:[1,0]
	v_pk_mul_f32 v[80:81], v[80:81], s[78:79] op_sel_hi:[1,0]
	v_pk_mul_f32 v[82:83], v[82:83], s[78:79] op_sel_hi:[1,0]
	v_pk_mul_f32 v[76:77], v[76:77], s[78:79] op_sel_hi:[1,0]
	v_pk_mul_f32 v[78:79], v[78:79], s[78:79] op_sel_hi:[1,0]
	v_cvt_pk_f16_f32 v152, v112, v113
	v_cvt_pk_f16_f32 v153, v114, v115
	v_cvt_pk_f16_f32 v154, v108, v109
	v_cvt_pk_f16_f32 v155, v110, v111
	global_store_dwordx4 v133, v[152:155], s[6:7] sc0 sc1 nt
	v_cvt_pk_f16_f32 v156, v80, v81
	v_cvt_pk_f16_f32 v157, v82, v83
	v_cvt_pk_f16_f32 v158, v76, v77
	v_cvt_pk_f16_f32 v159, v78, v79
	global_store_dwordx4 v133, v[156:159], s[6:7] offset:2048 sc0 sc1 nt
	s_add_u32 s6, s4, 0x8100
	s_addc_u32 s7, s5, 0
	v_pk_mul_f32 v[104:105], v[104:105], v[140:141] op_sel_hi:[1,0]
	v_pk_mul_f32 v[106:107], v[106:107], v[140:141] op_sel_hi:[1,0]
	v_pk_mul_f32 v[100:101], v[100:101], v[140:141] op_sel_hi:[1,0]
	v_pk_mul_f32 v[102:103], v[102:103], v[140:141] op_sel_hi:[1,0]
	v_pk_mul_f32 v[72:73], v[72:73], v[140:141] op_sel_hi:[1,0]
	v_pk_mul_f32 v[74:75], v[74:75], v[140:141] op_sel_hi:[1,0]
	v_pk_mul_f32 v[68:69], v[68:69], v[140:141] op_sel_hi:[1,0]
	v_pk_mul_f32 v[70:71], v[70:71], v[140:141] op_sel_hi:[1,0]
	v_pk_mul_f32 v[104:105], v[104:105], s[78:79] op_sel_hi:[1,0]
	v_pk_mul_f32 v[106:107], v[106:107], s[78:79] op_sel_hi:[1,0]
	v_pk_mul_f32 v[100:101], v[100:101], s[78:79] op_sel_hi:[1,0]
	v_pk_mul_f32 v[102:103], v[102:103], s[78:79] op_sel_hi:[1,0]
	v_pk_mul_f32 v[72:73], v[72:73], s[78:79] op_sel_hi:[1,0]
	v_pk_mul_f32 v[74:75], v[74:75], s[78:79] op_sel_hi:[1,0]
	v_pk_mul_f32 v[68:69], v[68:69], s[78:79] op_sel_hi:[1,0]
	v_pk_mul_f32 v[70:71], v[70:71], s[78:79] op_sel_hi:[1,0]
	v_cvt_pk_f16_f32 v160, v104, v105
	v_cvt_pk_f16_f32 v161, v106, v107
	v_cvt_pk_f16_f32 v162, v100, v101
	v_cvt_pk_f16_f32 v163, v102, v103
	global_store_dwordx4 v133, v[160:163], s[6:7] sc0 sc1 nt
	v_cvt_pk_f16_f32 v164, v72, v73
	v_cvt_pk_f16_f32 v165, v74, v75
	v_cvt_pk_f16_f32 v166, v68, v69
	v_cvt_pk_f16_f32 v167, v70, v71
	global_store_dwordx4 v133, v[164:167], s[6:7] offset:2048 sc0 sc1 nt
	s_add_u32 s6, s4, 0x20000
	s_addc_u32 s7, s5, 0
	v_pk_mul_f32 v[64:65], v[64:65], v[142:143] op_sel_hi:[1,0]
	v_pk_mul_f32 v[66:67], v[66:67], v[142:143] op_sel_hi:[1,0]
	v_pk_mul_f32 v[60:61], v[60:61], v[142:143] op_sel_hi:[1,0]
	v_pk_mul_f32 v[62:63], v[62:63], v[142:143] op_sel_hi:[1,0]
	v_pk_mul_f32 v[32:33], v[32:33], v[142:143] op_sel_hi:[1,0]
	v_pk_mul_f32 v[34:35], v[34:35], v[142:143] op_sel_hi:[1,0]
	v_pk_mul_f32 v[28:29], v[28:29], v[142:143] op_sel_hi:[1,0]
	v_pk_mul_f32 v[30:31], v[30:31], v[142:143] op_sel_hi:[1,0]
	v_pk_mul_f32 v[64:65], v[64:65], s[78:79] op_sel_hi:[1,0]
	v_pk_mul_f32 v[66:67], v[66:67], s[78:79] op_sel_hi:[1,0]
	v_pk_mul_f32 v[60:61], v[60:61], s[78:79] op_sel_hi:[1,0]
	v_pk_mul_f32 v[62:63], v[62:63], s[78:79] op_sel_hi:[1,0]
	v_pk_mul_f32 v[32:33], v[32:33], s[78:79] op_sel_hi:[1,0]
	v_pk_mul_f32 v[34:35], v[34:35], s[78:79] op_sel_hi:[1,0]
	v_pk_mul_f32 v[28:29], v[28:29], s[78:79] op_sel_hi:[1,0]
	v_pk_mul_f32 v[30:31], v[30:31], s[78:79] op_sel_hi:[1,0]
	v_cvt_pk_f16_f32 v152, v64, v65
	v_cvt_pk_f16_f32 v153, v66, v67
	v_cvt_pk_f16_f32 v154, v60, v61
	v_cvt_pk_f16_f32 v155, v62, v63
	global_store_dwordx4 v133, v[152:155], s[6:7] sc0 sc1 nt
	v_cvt_pk_f16_f32 v156, v32, v33
	v_cvt_pk_f16_f32 v157, v34, v35
	v_cvt_pk_f16_f32 v158, v28, v29
	v_cvt_pk_f16_f32 v159, v30, v31
	global_store_dwordx4 v133, v[156:159], s[6:7] offset:2048 sc0 sc1 nt
	s_add_u32 s6, s4, 0x20100
	s_addc_u32 s7, s5, 0
	v_pk_mul_f32 v[56:57], v[56:57], v[144:145] op_sel_hi:[1,0]
	v_pk_mul_f32 v[58:59], v[58:59], v[144:145] op_sel_hi:[1,0]
	v_pk_mul_f32 v[52:53], v[52:53], v[144:145] op_sel_hi:[1,0]
	v_pk_mul_f32 v[54:55], v[54:55], v[144:145] op_sel_hi:[1,0]
	v_pk_mul_f32 v[24:25], v[24:25], v[144:145] op_sel_hi:[1,0]
	v_pk_mul_f32 v[26:27], v[26:27], v[144:145] op_sel_hi:[1,0]
	v_pk_mul_f32 v[20:21], v[20:21], v[144:145] op_sel_hi:[1,0]
	v_pk_mul_f32 v[22:23], v[22:23], v[144:145] op_sel_hi:[1,0]
	v_pk_mul_f32 v[56:57], v[56:57], s[78:79] op_sel_hi:[1,0]
	v_pk_mul_f32 v[58:59], v[58:59], s[78:79] op_sel_hi:[1,0]
	v_pk_mul_f32 v[52:53], v[52:53], s[78:79] op_sel_hi:[1,0]
	v_pk_mul_f32 v[54:55], v[54:55], s[78:79] op_sel_hi:[1,0]
	v_pk_mul_f32 v[24:25], v[24:25], s[78:79] op_sel_hi:[1,0]
;     __device__ __forceinline__ void operator()(const f32x4 (&acc)[2][2][4][2], const Unit& u, int wr, int wc, int fr, int fq) const {
;     ...
;         const LAS int* tags = (const LAS int*)(rsc + 2048);
;         const int slot = (tags[0] == u.pm) ? 0 : (tags[1] == u.pm) ? 1 : -1;
;         const LAS float* rtab = (const LAS float*)rsc + (slot > 0 ? 256 : 0) + wr * 64 + fr;
; #pragma unroll
;         for (int ai = 0; ai < 2; ++ai)
; #pragma unroll
;             for (int m = 0; m < 4; ++m) {
;                 const int row = row0 + ai * HALF + m * 16;
;                 float rs;
;                 if (slot >= 0) rs = rtab[ai * HALF + m * 16];
;                 else {
;                     const f32x4 pv = *(const GAS f32x4*)(part + (size_t)row * 16 + fq * 4);
;                     float s = (pv[0] + pv[1]) + (pv[2] + pv[3]);
;                     s = row4_sum(s);
;                     rs = __builtin_amdgcn_rsqf(s * (1.0f / DM) + RMS_EPS);
;                 }
;                 f32x4 v[2][2];
; #pragma unroll
;                 for (int bj = 0; bj < 2; ++bj)
; #pragma unroll
;                     for (int n = 0; n < 2; ++n) v[bj][n] = acc[ai][bj][m][n] * rs;
;                 if (sec == 4 || sec == 5) {
;                     float ss = 0.f;
; #pragma unroll
;                     for (int bj = 0; bj < 2; ++bj)
; #pragma unroll
;                         for (int n = 0; n < 2; ++n) { const f32x4 x = v[bj][n]; ss += (x[0] * x[0] + x[1] * x[1]) + (x[2] * x[2] + x[3] * x[3]); }
;                     ss = row4_sum(ss);
;                     float rn = __builtin_amdgcn_rsqf(ss * (1.0f / 64.0f) + RMS_EPS);
;                     if (sec == 4) rn *= QS;
; #pragma unroll
;                     for (int bj = 0; bj < 2; ++bj)
; #pragma unroll
;                         for (int n = 0; n < 2; ++n) v[bj][n] = v[bj][n] * rn * gain[bj][n];
;                 } else if (sec == 0) {
; #pragma unroll
;                     for (int bj = 0; bj < 2; ++bj)
; #pragma unroll
;                         for (int n = 0; n < 2; ++n) v[bj][n] = v[bj][n] * QS;
;                 } else if (sec == 3 || sec == 7) {
; #pragma unroll
;                     for (int bj = 0; bj < 2; ++bj)
; #pragma unroll
;                         for (int n = 0; n < 2; ++n)
; #pragma unroll
;                             for (int e = 0; e < 4; ++e) v[bj][n][e] = silu_f(v[bj][n][e]);
;                 }
	v_pk_mul_f32 v[26:27], v[26:27], s[78:79] op_sel_hi:[1,0]
	v_pk_mul_f32 v[20:21], v[20:21], s[78:79] op_sel_hi:[1,0]
	v_pk_mul_f32 v[22:23], v[22:23], s[78:79] op_sel_hi:[1,0]
	v_cvt_pk_f16_f32 v160, v56, v57
	v_cvt_pk_f16_f32 v161, v58, v59
	v_cvt_pk_f16_f32 v162, v52, v53
	v_cvt_pk_f16_f32 v163, v54, v55
	global_store_dwordx4 v133, v[160:163], s[6:7] sc0 sc1 nt
	v_cvt_pk_f16_f32 v164, v24, v25
	v_cvt_pk_f16_f32 v165, v26, v27
	v_cvt_pk_f16_f32 v166, v20, v21
	v_cvt_pk_f16_f32 v167, v22, v23
	global_store_dwordx4 v133, v[164:167], s[6:7] offset:2048 sc0 sc1 nt
	s_add_u32 s6, s4, 0x28000
	s_addc_u32 s7, s5, 0
	v_pk_mul_f32 v[48:49], v[48:49], v[146:147] op_sel_hi:[1,0]
	v_pk_mul_f32 v[50:51], v[50:51], v[146:147] op_sel_hi:[1,0]
	v_pk_mul_f32 v[44:45], v[44:45], v[146:147] op_sel_hi:[1,0]
	v_pk_mul_f32 v[46:47], v[46:47], v[146:147] op_sel_hi:[1,0]
	v_pk_mul_f32 v[16:17], v[16:17], v[146:147] op_sel_hi:[1,0]
	v_pk_mul_f32 v[18:19], v[18:19], v[146:147] op_sel_hi:[1,0]
	v_pk_mul_f32 v[12:13], v[12:13], v[146:147] op_sel_hi:[1,0]
	v_pk_mul_f32 v[14:15], v[14:15], v[146:147] op_sel_hi:[1,0]
	v_pk_mul_f32 v[48:49], v[48:49], s[78:79] op_sel_hi:[1,0]
	v_pk_mul_f32 v[50:51], v[50:51], s[78:79] op_sel_hi:[1,0]
	v_pk_mul_f32 v[44:45], v[44:45], s[78:79] op_sel_hi:[1,0]
	v_pk_mul_f32 v[46:47], v[46:47], s[78:79] op_sel_hi:[1,0]
	v_pk_mul_f32 v[16:17], v[16:17], s[78:79] op_sel_hi:[1,0]
	v_pk_mul_f32 v[18:19], v[18:19], s[78:79] op_sel_hi:[1,0]
	v_pk_mul_f32 v[12:13], v[12:13], s[78:79] op_sel_hi:[1,0]
	v_pk_mul_f32 v[14:15], v[14:15], s[78:79] op_sel_hi:[1,0]
	v_cvt_pk_f16_f32 v152, v48, v49
	v_cvt_pk_f16_f32 v153, v50, v51
	v_cvt_pk_f16_f32 v154, v44, v45
	v_cvt_pk_f16_f32 v155, v46, v47
	global_store_dwordx4 v133, v[152:155], s[6:7] sc0 sc1 nt
	v_cvt_pk_f16_f32 v156, v16, v17
	v_cvt_pk_f16_f32 v157, v18, v19
	v_cvt_pk_f16_f32 v158, v12, v13
	v_cvt_pk_f16_f32 v159, v14, v15
	global_store_dwordx4 v133, v[156:159], s[6:7] offset:2048 sc0 sc1 nt
	s_add_u32 s6, s4, 0x28100
	s_addc_u32 s7, s5, 0
	v_pk_mul_f32 v[40:41], v[40:41], v[148:149] op_sel_hi:[1,0]
	v_pk_mul_f32 v[42:43], v[42:43], v[148:149] op_sel_hi:[1,0]
	v_pk_mul_f32 v[36:37], v[36:37], v[148:149] op_sel_hi:[1,0]
	v_pk_mul_f32 v[38:39], v[38:39], v[148:149] op_sel_hi:[1,0]
	v_pk_mul_f32 v[8:9], v[8:9], v[148:149] op_sel_hi:[1,0]
	v_pk_mul_f32 v[10:11], v[10:11], v[148:149] op_sel_hi:[1,0]
	v_pk_mul_f32 v[4:5], v[4:5], v[148:149] op_sel_hi:[1,0]
	v_pk_mul_f32 v[6:7], v[6:7], v[148:149] op_sel_hi:[1,0]
	v_pk_mul_f32 v[40:41], v[40:41], s[78:79] op_sel_hi:[1,0]
	v_pk_mul_f32 v[42:43], v[42:43], s[78:79] op_sel_hi:[1,0]
	v_pk_mul_f32 v[36:37], v[36:37], s[78:79] op_sel_hi:[1,0]
	v_pk_mul_f32 v[38:39], v[38:39], s[78:79] op_sel_hi:[1,0]
	v_pk_mul_f32 v[8:9], v[8:9], s[78:79] op_sel_hi:[1,0]
	v_pk_mul_f32 v[10:11], v[10:11], s[78:79] op_sel_hi:[1,0]
	v_pk_mul_f32 v[4:5], v[4:5], s[78:79] op_sel_hi:[1,0]
	v_pk_mul_f32 v[6:7], v[6:7], s[78:79] op_sel_hi:[1,0]
	v_cvt_pk_f16_f32 v160, v40, v41
	v_cvt_pk_f16_f32 v161, v42, v43
	v_cvt_pk_f16_f32 v162, v36, v37
	v_cvt_pk_f16_f32 v163, v38, v39
	global_store_dwordx4 v133, v[160:163], s[6:7] sc0 sc1 nt
	v_cvt_pk_f16_f32 v164, v8, v9
	v_cvt_pk_f16_f32 v165, v10, v11
	v_cvt_pk_f16_f32 v166, v4, v5
	v_cvt_pk_f16_f32 v167, v6, v7
	global_store_dwordx4 v133, v[164:167], s[6:7] offset:2048 sc0 sc1 nt
	s_branch .Lepi_done_g1
.Lepi_silu:
	s_and_b32 s0, s70, 1
	s_lshl_b32 s0, s0, 10
	v_add_u32_e32 v132, s0, v219
	ds_read_b32 v134, v132
	ds_read_b32 v136, v132 offset:64
	ds_read_b32 v138, v132 offset:128
	ds_read_b32 v140, v132 offset:192
	ds_read_b32 v142, v132 offset:512
	ds_read_b32 v144, v132 offset:576
	ds_read_b32 v146, v132 offset:640
	ds_read_b32 v148, v132 offset:704
	s_lshr_b32 s0, s69, 2
	s_and_b32 s1, s69, 1
	v_lshrrev_b32_e32 v2, 6, v187
	v_lshrrev_b32_e32 v133, 3, v220
	v_lshl_add_u32 v133, v2, 7, v133
	v_and_b32_e32 v2, 15, v187
	v_lshlrev_b32_e32 v133, 8, v133
	v_lshl_add_u32 v133, v2, 3, v133
	v_lshlrev_b32_e32 v133, 1, v133
	s_lshl_b32 s0, s0, 25
	s_lshl_b32 s1, s1, 14
	s_add_u32 s0, s0, s1
	s_lshl_b32 s1, s68, 18
	s_add_u32 s0, s0, s1
	s_add_u32 s4, s82, s0
	s_addc_u32 s5, s83, 0
	s_waitcnt lgkmcnt(0)
	s_mov_b32 s6, s4
	s_mov_b32 s7, s5
	v_pk_mul_f32 v[128:129], v[128:129], v[134:135] op_sel_hi:[1,0]
	v_pk_mul_f32 v[130:131], v[130:131], v[134:135] op_sel_hi:[1,0]
	v_pk_mul_f32 v[124:125], v[124:125], v[134:135] op_sel_hi:[1,0]
	v_pk_mul_f32 v[126:127], v[126:127], v[134:135] op_sel_hi:[1,0]
	v_pk_mul_f32 v[96:97], v[96:97], v[134:135] op_sel_hi:[1,0]
	v_pk_mul_f32 v[98:99], v[98:99], v[134:135] op_sel_hi:[1,0]
	v_pk_mul_f32 v[92:93], v[92:93], v[134:135] op_sel_hi:[1,0]
	v_pk_mul_f32 v[94:95], v[94:95], v[134:135] op_sel_hi:[1,0]
	v_mul_f32_e32 v168, 0xbfb8aa3b, v128
	v_mul_f32_e32 v169, 0xbfb8aa3b, v129
	v_mul_f32_e32 v170, 0xbfb8aa3b, v130
	v_mul_f32_e32 v171, 0xbfb8aa3b, v131
	v_exp_f32_e32 v168, v168
	v_exp_f32_e32 v169, v169
	v_exp_f32_e32 v170, v170
	v_exp_f32_e32 v171, v171
	v_add_f32_e32 v168, 1.0, v168
	v_add_f32_e32 v169, 1.0, v169
	v_add_f32_e32 v170, 1.0, v170
	v_add_f32_e32 v171, 1.0, v171
	v_rcp_f32_e32 v168, v168
	v_rcp_f32_e32 v169, v169
	v_rcp_f32_e32 v170, v170
	v_rcp_f32_e32 v171, v171
	v_pk_mul_f32 v[128:129], v[128:129], v[168:169]
	v_pk_mul_f32 v[130:131], v[130:131], v[170:171]
	v_mul_f32_e32 v168, 0xbfb8aa3b, v124
	v_mul_f32_e32 v169, 0xbfb8aa3b, v125
	v_mul_f32_e32 v170, 0xbfb8aa3b, v126
	v_mul_f32_e32 v171, 0xbfb8aa3b, v127
	v_exp_f32_e32 v168, v168
	v_exp_f32_e32 v169, v169
	v_exp_f32_e32 v170, v170
	v_exp_f32_e32 v171, v171
	v_add_f32_e32 v168, 1.0, v168
	v_add_f32_e32 v169, 1.0, v169
	v_add_f32_e32 v170, 1.0, v170
; #define GAS __attribute__((address_space(1)))
; __host__ __device__ __forceinline__ size_t bl512(size_t row, int col) { return ((row >> 5) * 64 + (size_t)(col >> 3)) * 256 + (row & 31) * 8 + (col & 7); }
; __device__ __forceinline__ float silu_f(float v) { return v * __builtin_amdgcn_rcpf(1.0f + __builtin_amdgcn_exp2f(-v * LOG2E)); }
;     __device__ __forceinline__ void operator()(const f32x4 (&acc)[2][2][4][2], const Unit& u, int wr, int wc, int fr, int fq) const {
;     ...
;                 f32x4 v[2][2];
; #pragma unroll
;                 for (int bj = 0; bj < 2; ++bj)
; #pragma unroll
;                     for (int n = 0; n < 2; ++n) v[bj][n] = acc[ai][bj][m][n] * rs;
;                 if (sec == 4 || sec == 5) {
;                     float ss = 0.f;
; #pragma unroll
;                     for (int bj = 0; bj < 2; ++bj)
; #pragma unroll
;                         for (int n = 0; n < 2; ++n) { const f32x4 x = v[bj][n]; ss += (x[0] * x[0] + x[1] * x[1]) + (x[2] * x[2] + x[3] * x[3]); }
;                     ss = row4_sum(ss);
;                     float rn = __builtin_amdgcn_rsqf(ss * (1.0f / 64.0f) + RMS_EPS);
;                     if (sec == 4) rn *= QS;
; #pragma unroll
;                     for (int bj = 0; bj < 2; ++bj)
; #pragma unroll
;                         for (int n = 0; n < 2; ++n) v[bj][n] = v[bj][n] * rn * gain[bj][n];
;                 } else if (sec == 0) {
; #pragma unroll
;                     for (int bj = 0; bj < 2; ++bj)
; #pragma unroll
;                         for (int n = 0; n < 2; ++n) v[bj][n] = v[bj][n] * QS;
;                 } else if (sec == 3 || sec == 7) {
; #pragma unroll
;                     for (int bj = 0; bj < 2; ++bj)
; #pragma unroll
;                         for (int n = 0; n < 2; ++n)
; #pragma unroll
;                             for (int e = 0; e < 4; ++e) v[bj][n][e] = silu_f(v[bj][n][e]);
;                 }
;                 GAS f16* rowp = isqg ? QG + (size_t)dsec * QG_SEC + bl512((size_t)row, cs) : KV + (size_t)row * KVW + dsec * 512 + cs;
; #pragma unroll
;                 for (int bj = 0; bj < 2; ++bj) {
;                     u32x4 w; w.x = pkh(v[bj][0][0], v[bj][0][1]); w.y = pkh(v[bj][0][2], v[bj][0][3]); w.z = pkh(v[bj][1][0], v[bj][1][1]); w.w = pkh(v[bj][1][2], v[bj][1][3]);
;                     *(GAS u32x4*)(rowp + bjstep * bj) = w;
;                 }
	v_add_f32_e32 v171, 1.0, v171
	v_rcp_f32_e32 v168, v168
	v_rcp_f32_e32 v169, v169
	v_rcp_f32_e32 v170, v170
	v_rcp_f32_e32 v171, v171
	v_pk_mul_f32 v[124:125], v[124:125], v[168:169]
	v_pk_mul_f32 v[126:127], v[126:127], v[170:171]
	v_mul_f32_e32 v168, 0xbfb8aa3b, v96
	v_mul_f32_e32 v169, 0xbfb8aa3b, v97
	v_mul_f32_e32 v170, 0xbfb8aa3b, v98
	v_mul_f32_e32 v171, 0xbfb8aa3b, v99
	v_exp_f32_e32 v168, v168
	v_exp_f32_e32 v169, v169
	v_exp_f32_e32 v170, v170
	v_exp_f32_e32 v171, v171
	v_add_f32_e32 v168, 1.0, v168
	v_add_f32_e32 v169, 1.0, v169
	v_add_f32_e32 v170, 1.0, v170
	v_add_f32_e32 v171, 1.0, v171
	v_rcp_f32_e32 v168, v168
	v_rcp_f32_e32 v169, v169
	v_rcp_f32_e32 v170, v170
	v_rcp_f32_e32 v171, v171
	v_pk_mul_f32 v[96:97], v[96:97], v[168:169]
	v_pk_mul_f32 v[98:99], v[98:99], v[170:171]
	v_mul_f32_e32 v168, 0xbfb8aa3b, v92
	v_mul_f32_e32 v169, 0xbfb8aa3b, v93
	v_mul_f32_e32 v170, 0xbfb8aa3b, v94
	v_mul_f32_e32 v171, 0xbfb8aa3b, v95
	v_exp_f32_e32 v168, v168
	v_exp_f32_e32 v169, v169
	v_exp_f32_e32 v170, v170
	v_exp_f32_e32 v171, v171
	v_add_f32_e32 v168, 1.0, v168
	v_add_f32_e32 v169, 1.0, v169
	v_add_f32_e32 v170, 1.0, v170
	v_add_f32_e32 v171, 1.0, v171
	v_rcp_f32_e32 v168, v168
	v_rcp_f32_e32 v169, v169
	v_rcp_f32_e32 v170, v170
	v_rcp_f32_e32 v171, v171
	v_pk_mul_f32 v[92:93], v[92:93], v[168:169]
	v_pk_mul_f32 v[94:95], v[94:95], v[170:171]
	v_cvt_pk_f16_f32 v152, v128, v129
	v_cvt_pk_f16_f32 v153, v130, v131
	v_cvt_pk_f16_f32 v154, v124, v125
	v_cvt_pk_f16_f32 v155, v126, v127
	global_store_dwordx4 v133, v[152:155], s[6:7] sc0 sc1 nt
	v_cvt_pk_f16_f32 v156, v96, v97
	v_cvt_pk_f16_f32 v157, v98, v99
	v_cvt_pk_f16_f32 v158, v92, v93
	v_cvt_pk_f16_f32 v159, v94, v95
	global_store_dwordx4 v133, v[156:159], s[6:7] offset:2048 sc0 sc1 nt
	s_add_u32 s6, s4, 0x100
	s_addc_u32 s7, s5, 0
	v_pk_mul_f32 v[120:121], v[120:121], v[136:137] op_sel_hi:[1,0]
	v_pk_mul_f32 v[122:123], v[122:123], v[136:137] op_sel_hi:[1,0]
	v_pk_mul_f32 v[116:117], v[116:117], v[136:137] op_sel_hi:[1,0]
	v_pk_mul_f32 v[118:119], v[118:119], v[136:137] op_sel_hi:[1,0]
	v_pk_mul_f32 v[88:89], v[88:89], v[136:137] op_sel_hi:[1,0]
	v_pk_mul_f32 v[90:91], v[90:91], v[136:137] op_sel_hi:[1,0]
	v_pk_mul_f32 v[84:85], v[84:85], v[136:137] op_sel_hi:[1,0]
	v_pk_mul_f32 v[86:87], v[86:87], v[136:137] op_sel_hi:[1,0]
	v_mul_f32_e32 v168, 0xbfb8aa3b, v120
	v_mul_f32_e32 v169, 0xbfb8aa3b, v121
	v_mul_f32_e32 v170, 0xbfb8aa3b, v122
	v_mul_f32_e32 v171, 0xbfb8aa3b, v123
	v_exp_f32_e32 v168, v168
	v_exp_f32_e32 v169, v169
	v_exp_f32_e32 v170, v170
	v_exp_f32_e32 v171, v171
	v_add_f32_e32 v168, 1.0, v168
	v_add_f32_e32 v169, 1.0, v169
	v_add_f32_e32 v170, 1.0, v170
	v_add_f32_e32 v171, 1.0, v171
	v_rcp_f32_e32 v168, v168
	v_rcp_f32_e32 v169, v169
	v_rcp_f32_e32 v170, v170
	v_rcp_f32_e32 v171, v171
	v_pk_mul_f32 v[120:121], v[120:121], v[168:169]
	v_pk_mul_f32 v[122:123], v[122:123], v[170:171]
	v_mul_f32_e32 v168, 0xbfb8aa3b, v116
	v_mul_f32_e32 v169, 0xbfb8aa3b, v117
	v_mul_f32_e32 v170, 0xbfb8aa3b, v118
	v_mul_f32_e32 v171, 0xbfb8aa3b, v119
	v_exp_f32_e32 v168, v168
	v_exp_f32_e32 v169, v169
	v_exp_f32_e32 v170, v170
	v_exp_f32_e32 v171, v171
	v_add_f32_e32 v168, 1.0, v168
	v_add_f32_e32 v169, 1.0, v169
	v_add_f32_e32 v170, 1.0, v170
	v_add_f32_e32 v171, 1.0, v171
	v_rcp_f32_e32 v168, v168
	v_rcp_f32_e32 v169, v169
	v_rcp_f32_e32 v170, v170
	v_rcp_f32_e32 v171, v171
	v_pk_mul_f32 v[116:117], v[116:117], v[168:169]
	v_pk_mul_f32 v[118:119], v[118:119], v[170:171]
	v_mul_f32_e32 v168, 0xbfb8aa3b, v88
	v_mul_f32_e32 v169, 0xbfb8aa3b, v89
	v_mul_f32_e32 v170, 0xbfb8aa3b, v90
	v_mul_f32_e32 v171, 0xbfb8aa3b, v91
	v_exp_f32_e32 v168, v168
	v_exp_f32_e32 v169, v169
	v_exp_f32_e32 v170, v170
	v_exp_f32_e32 v171, v171
	v_add_f32_e32 v168, 1.0, v168
	v_add_f32_e32 v169, 1.0, v169
	v_add_f32_e32 v170, 1.0, v170
	v_add_f32_e32 v171, 1.0, v171
	v_rcp_f32_e32 v168, v168
	v_rcp_f32_e32 v169, v169
	v_rcp_f32_e32 v170, v170
	v_rcp_f32_e32 v171, v171
	v_pk_mul_f32 v[88:89], v[88:89], v[168:169]
	v_pk_mul_f32 v[90:91], v[90:91], v[170:171]
	v_mul_f32_e32 v168, 0xbfb8aa3b, v84
	v_mul_f32_e32 v169, 0xbfb8aa3b, v85
	v_mul_f32_e32 v170, 0xbfb8aa3b, v86
	v_mul_f32_e32 v171, 0xbfb8aa3b, v87
	v_exp_f32_e32 v168, v168
	v_exp_f32_e32 v169, v169
	v_exp_f32_e32 v170, v170
	v_exp_f32_e32 v171, v171
	v_add_f32_e32 v168, 1.0, v168
	v_add_f32_e32 v169, 1.0, v169
	v_add_f32_e32 v170, 1.0, v170
	v_add_f32_e32 v171, 1.0, v171
	v_rcp_f32_e32 v168, v168
	v_rcp_f32_e32 v169, v169
	v_rcp_f32_e32 v170, v170
	v_rcp_f32_e32 v171, v171
	v_pk_mul_f32 v[84:85], v[84:85], v[168:169]
	v_pk_mul_f32 v[86:87], v[86:87], v[170:171]
	v_cvt_pk_f16_f32 v160, v120, v121
	v_cvt_pk_f16_f32 v161, v122, v123
	v_cvt_pk_f16_f32 v162, v116, v117
	v_cvt_pk_f16_f32 v163, v118, v119
	global_store_dwordx4 v133, v[160:163], s[6:7] sc0 sc1 nt
	v_cvt_pk_f16_f32 v164, v88, v89
	v_cvt_pk_f16_f32 v165, v90, v91
	v_cvt_pk_f16_f32 v166, v84, v85
	v_cvt_pk_f16_f32 v167, v86, v87
	global_store_dwordx4 v133, v[164:167], s[6:7] offset:2048 sc0 sc1 nt
	s_add_u32 s6, s4, 0x8000
	s_addc_u32 s7, s5, 0
	v_pk_mul_f32 v[112:113], v[112:113], v[138:139] op_sel_hi:[1,0]
	v_pk_mul_f32 v[114:115], v[114:115], v[138:139] op_sel_hi:[1,0]
	v_pk_mul_f32 v[108:109], v[108:109], v[138:139] op_sel_hi:[1,0]
	v_pk_mul_f32 v[110:111], v[110:111], v[138:139] op_sel_hi:[1,0]
	v_pk_mul_f32 v[80:81], v[80:81], v[138:139] op_sel_hi:[1,0]
	v_pk_mul_f32 v[82:83], v[82:83], v[138:139] op_sel_hi:[1,0]
	v_pk_mul_f32 v[76:77], v[76:77], v[138:139] op_sel_hi:[1,0]
	v_pk_mul_f32 v[78:79], v[78:79], v[138:139] op_sel_hi:[1,0]
	v_mul_f32_e32 v168, 0xbfb8aa3b, v112
	v_mul_f32_e32 v169, 0xbfb8aa3b, v113
; #define GAS __attribute__((address_space(1)))
; __host__ __device__ __forceinline__ size_t bl512(size_t row, int col) { return ((row >> 5) * 64 + (size_t)(col >> 3)) * 256 + (row & 31) * 8 + (col & 7); }
; __device__ __forceinline__ float silu_f(float v) { return v * __builtin_amdgcn_rcpf(1.0f + __builtin_amdgcn_exp2f(-v * LOG2E)); }
;     __device__ __forceinline__ void operator()(const f32x4 (&acc)[2][2][4][2], const Unit& u, int wr, int wc, int fr, int fq) const {
;     ...
;                 f32x4 v[2][2];
; #pragma unroll
;                 for (int bj = 0; bj < 2; ++bj)
; #pragma unroll
;                     for (int n = 0; n < 2; ++n) v[bj][n] = acc[ai][bj][m][n] * rs;
;                 if (sec == 4 || sec == 5) {
;                     float ss = 0.f;
; #pragma unroll
;                     for (int bj = 0; bj < 2; ++bj)
; #pragma unroll
;                         for (int n = 0; n < 2; ++n) { const f32x4 x = v[bj][n]; ss += (x[0] * x[0] + x[1] * x[1]) + (x[2] * x[2] + x[3] * x[3]); }
;                     ss = row4_sum(ss);
;                     float rn = __builtin_amdgcn_rsqf(ss * (1.0f / 64.0f) + RMS_EPS);
;                     if (sec == 4) rn *= QS;
; #pragma unroll
;                     for (int bj = 0; bj < 2; ++bj)
; #pragma unroll
;                         for (int n = 0; n < 2; ++n) v[bj][n] = v[bj][n] * rn * gain[bj][n];
;                 } else if (sec == 0) {
; #pragma unroll
;                     for (int bj = 0; bj < 2; ++bj)
; #pragma unroll
;                         for (int n = 0; n < 2; ++n) v[bj][n] = v[bj][n] * QS;
;                 } else if (sec == 3 || sec == 7) {
; #pragma unroll
;                     for (int bj = 0; bj < 2; ++bj)
; #pragma unroll
;                         for (int n = 0; n < 2; ++n)
; #pragma unroll
;                             for (int e = 0; e < 4; ++e) v[bj][n][e] = silu_f(v[bj][n][e]);
;                 }
;                 GAS f16* rowp = isqg ? QG + (size_t)dsec * QG_SEC + bl512((size_t)row, cs) : KV + (size_t)row * KVW + dsec * 512 + cs;
; #pragma unroll
;                 for (int bj = 0; bj < 2; ++bj) {
;                     u32x4 w; w.x = pkh(v[bj][0][0], v[bj][0][1]); w.y = pkh(v[bj][0][2], v[bj][0][3]); w.z = pkh(v[bj][1][0], v[bj][1][1]); w.w = pkh(v[bj][1][2], v[bj][1][3]);
;                     *(GAS u32x4*)(rowp + bjstep * bj) = w;
;                 }
	v_mul_f32_e32 v170, 0xbfb8aa3b, v114
	v_mul_f32_e32 v171, 0xbfb8aa3b, v115
	v_exp_f32_e32 v168, v168
	v_exp_f32_e32 v169, v169
	v_exp_f32_e32 v170, v170
	v_exp_f32_e32 v171, v171
	v_add_f32_e32 v168, 1.0, v168
	v_add_f32_e32 v169, 1.0, v169
	v_add_f32_e32 v170, 1.0, v170
	v_add_f32_e32 v171, 1.0, v171
	v_rcp_f32_e32 v168, v168
	v_rcp_f32_e32 v169, v169
	v_rcp_f32_e32 v170, v170
	v_rcp_f32_e32 v171, v171
	v_pk_mul_f32 v[112:113], v[112:113], v[168:169]
	v_pk_mul_f32 v[114:115], v[114:115], v[170:171]
	v_mul_f32_e32 v168, 0xbfb8aa3b, v108
	v_mul_f32_e32 v169, 0xbfb8aa3b, v109
	v_mul_f32_e32 v170, 0xbfb8aa3b, v110
	v_mul_f32_e32 v171, 0xbfb8aa3b, v111
	v_exp_f32_e32 v168, v168
	v_exp_f32_e32 v169, v169
	v_exp_f32_e32 v170, v170
	v_exp_f32_e32 v171, v171
	v_add_f32_e32 v168, 1.0, v168
	v_add_f32_e32 v169, 1.0, v169
	v_add_f32_e32 v170, 1.0, v170
	v_add_f32_e32 v171, 1.0, v171
	v_rcp_f32_e32 v168, v168
	v_rcp_f32_e32 v169, v169
	v_rcp_f32_e32 v170, v170
	v_rcp_f32_e32 v171, v171
	v_pk_mul_f32 v[108:109], v[108:109], v[168:169]
	v_pk_mul_f32 v[110:111], v[110:111], v[170:171]
	v_mul_f32_e32 v168, 0xbfb8aa3b, v80
	v_mul_f32_e32 v169, 0xbfb8aa3b, v81
	v_mul_f32_e32 v170, 0xbfb8aa3b, v82
	v_mul_f32_e32 v171, 0xbfb8aa3b, v83
	v_exp_f32_e32 v168, v168
	v_exp_f32_e32 v169, v169
	v_exp_f32_e32 v170, v170
	v_exp_f32_e32 v171, v171
	v_add_f32_e32 v168, 1.0, v168
	v_add_f32_e32 v169, 1.0, v169
	v_add_f32_e32 v170, 1.0, v170
	v_add_f32_e32 v171, 1.0, v171
	v_rcp_f32_e32 v168, v168
	v_rcp_f32_e32 v169, v169
	v_rcp_f32_e32 v170, v170
	v_rcp_f32_e32 v171, v171
	v_pk_mul_f32 v[80:81], v[80:81], v[168:169]
	v_pk_mul_f32 v[82:83], v[82:83], v[170:171]
	v_mul_f32_e32 v168, 0xbfb8aa3b, v76
	v_mul_f32_e32 v169, 0xbfb8aa3b, v77
	v_mul_f32_e32 v170, 0xbfb8aa3b, v78
	v_mul_f32_e32 v171, 0xbfb8aa3b, v79
	v_exp_f32_e32 v168, v168
	v_exp_f32_e32 v169, v169
	v_exp_f32_e32 v170, v170
	v_exp_f32_e32 v171, v171
	v_add_f32_e32 v168, 1.0, v168
	v_add_f32_e32 v169, 1.0, v169
	v_add_f32_e32 v170, 1.0, v170
	v_add_f32_e32 v171, 1.0, v171
	v_rcp_f32_e32 v168, v168
	v_rcp_f32_e32 v169, v169
	v_rcp_f32_e32 v170, v170
	v_rcp_f32_e32 v171, v171
	v_pk_mul_f32 v[76:77], v[76:77], v[168:169]
	v_pk_mul_f32 v[78:79], v[78:79], v[170:171]
	v_cvt_pk_f16_f32 v152, v112, v113
	v_cvt_pk_f16_f32 v153, v114, v115
	v_cvt_pk_f16_f32 v154, v108, v109
	v_cvt_pk_f16_f32 v155, v110, v111
	global_store_dwordx4 v133, v[152:155], s[6:7] sc0 sc1 nt
	v_cvt_pk_f16_f32 v156, v80, v81
	v_cvt_pk_f16_f32 v157, v82, v83
	v_cvt_pk_f16_f32 v158, v76, v77
	v_cvt_pk_f16_f32 v159, v78, v79
	global_store_dwordx4 v133, v[156:159], s[6:7] offset:2048 sc0 sc1 nt
	s_add_u32 s6, s4, 0x8100
	s_addc_u32 s7, s5, 0
	v_pk_mul_f32 v[104:105], v[104:105], v[140:141] op_sel_hi:[1,0]
	v_pk_mul_f32 v[106:107], v[106:107], v[140:141] op_sel_hi:[1,0]
	v_pk_mul_f32 v[100:101], v[100:101], v[140:141] op_sel_hi:[1,0]
	v_pk_mul_f32 v[102:103], v[102:103], v[140:141] op_sel_hi:[1,0]
	v_pk_mul_f32 v[72:73], v[72:73], v[140:141] op_sel_hi:[1,0]
	v_pk_mul_f32 v[74:75], v[74:75], v[140:141] op_sel_hi:[1,0]
	v_pk_mul_f32 v[68:69], v[68:69], v[140:141] op_sel_hi:[1,0]
	v_pk_mul_f32 v[70:71], v[70:71], v[140:141] op_sel_hi:[1,0]
	v_mul_f32_e32 v168, 0xbfb8aa3b, v104
	v_mul_f32_e32 v169, 0xbfb8aa3b, v105
	v_mul_f32_e32 v170, 0xbfb8aa3b, v106
	v_mul_f32_e32 v171, 0xbfb8aa3b, v107
	v_exp_f32_e32 v168, v168
	v_exp_f32_e32 v169, v169
	v_exp_f32_e32 v170, v170
	v_exp_f32_e32 v171, v171
	v_add_f32_e32 v168, 1.0, v168
	v_add_f32_e32 v169, 1.0, v169
	v_add_f32_e32 v170, 1.0, v170
	v_add_f32_e32 v171, 1.0, v171
	v_rcp_f32_e32 v168, v168
	v_rcp_f32_e32 v169, v169
	v_rcp_f32_e32 v170, v170
	v_rcp_f32_e32 v171, v171
	v_pk_mul_f32 v[104:105], v[104:105], v[168:169]
	v_pk_mul_f32 v[106:107], v[106:107], v[170:171]
	v_mul_f32_e32 v168, 0xbfb8aa3b, v100
	v_mul_f32_e32 v169, 0xbfb8aa3b, v101
	v_mul_f32_e32 v170, 0xbfb8aa3b, v102
	v_mul_f32_e32 v171, 0xbfb8aa3b, v103
	v_exp_f32_e32 v168, v168
	v_exp_f32_e32 v169, v169
	v_exp_f32_e32 v170, v170
	v_exp_f32_e32 v171, v171
	v_add_f32_e32 v168, 1.0, v168
	v_add_f32_e32 v169, 1.0, v169
	v_add_f32_e32 v170, 1.0, v170
	v_add_f32_e32 v171, 1.0, v171
	v_rcp_f32_e32 v168, v168
	v_rcp_f32_e32 v169, v169
	v_rcp_f32_e32 v170, v170
	v_rcp_f32_e32 v171, v171
	v_pk_mul_f32 v[100:101], v[100:101], v[168:169]
	v_pk_mul_f32 v[102:103], v[102:103], v[170:171]
	v_mul_f32_e32 v168, 0xbfb8aa3b, v72
	v_mul_f32_e32 v169, 0xbfb8aa3b, v73
	v_mul_f32_e32 v170, 0xbfb8aa3b, v74
	v_mul_f32_e32 v171, 0xbfb8aa3b, v75
	v_exp_f32_e32 v168, v168
	v_exp_f32_e32 v169, v169
	v_exp_f32_e32 v170, v170
	v_exp_f32_e32 v171, v171
	v_add_f32_e32 v168, 1.0, v168
	v_add_f32_e32 v169, 1.0, v169
	v_add_f32_e32 v170, 1.0, v170
	v_add_f32_e32 v171, 1.0, v171
	v_rcp_f32_e32 v168, v168
	v_rcp_f32_e32 v169, v169
	v_rcp_f32_e32 v170, v170
	v_rcp_f32_e32 v171, v171
	v_pk_mul_f32 v[72:73], v[72:73], v[168:169]
	v_pk_mul_f32 v[74:75], v[74:75], v[170:171]
	v_mul_f32_e32 v168, 0xbfb8aa3b, v68
	v_mul_f32_e32 v169, 0xbfb8aa3b, v69
	v_mul_f32_e32 v170, 0xbfb8aa3b, v70
	v_mul_f32_e32 v171, 0xbfb8aa3b, v71
	v_exp_f32_e32 v168, v168
	v_exp_f32_e32 v169, v169
	v_exp_f32_e32 v170, v170
	v_exp_f32_e32 v171, v171
	v_add_f32_e32 v168, 1.0, v168
	v_add_f32_e32 v169, 1.0, v169
	v_add_f32_e32 v170, 1.0, v170
	v_add_f32_e32 v171, 1.0, v171
	v_rcp_f32_e32 v168, v168
	v_rcp_f32_e32 v169, v169
	v_rcp_f32_e32 v170, v170
	v_rcp_f32_e32 v171, v171
	v_pk_mul_f32 v[68:69], v[68:69], v[168:169]
	v_pk_mul_f32 v[70:71], v[70:71], v[170:171]
	v_cvt_pk_f16_f32 v160, v104, v105
	v_cvt_pk_f16_f32 v161, v106, v107
	v_cvt_pk_f16_f32 v162, v100, v101
	v_cvt_pk_f16_f32 v163, v102, v103
; #define GAS __attribute__((address_space(1)))
; __host__ __device__ __forceinline__ size_t bl512(size_t row, int col) { return ((row >> 5) * 64 + (size_t)(col >> 3)) * 256 + (row & 31) * 8 + (col & 7); }
; __device__ __forceinline__ float silu_f(float v) { return v * __builtin_amdgcn_rcpf(1.0f + __builtin_amdgcn_exp2f(-v * LOG2E)); }
;     __device__ __forceinline__ void operator()(const f32x4 (&acc)[2][2][4][2], const Unit& u, int wr, int wc, int fr, int fq) const {
;     ...
;                 f32x4 v[2][2];
; #pragma unroll
;                 for (int bj = 0; bj < 2; ++bj)
; #pragma unroll
;                     for (int n = 0; n < 2; ++n) v[bj][n] = acc[ai][bj][m][n] * rs;
;                 if (sec == 4 || sec == 5) {
;                     float ss = 0.f;
; #pragma unroll
;                     for (int bj = 0; bj < 2; ++bj)
; #pragma unroll
;                         for (int n = 0; n < 2; ++n) { const f32x4 x = v[bj][n]; ss += (x[0] * x[0] + x[1] * x[1]) + (x[2] * x[2] + x[3] * x[3]); }
;                     ss = row4_sum(ss);
;                     float rn = __builtin_amdgcn_rsqf(ss * (1.0f / 64.0f) + RMS_EPS);
;                     if (sec == 4) rn *= QS;
; #pragma unroll
;                     for (int bj = 0; bj < 2; ++bj)
; #pragma unroll
;                         for (int n = 0; n < 2; ++n) v[bj][n] = v[bj][n] * rn * gain[bj][n];
;                 } else if (sec == 0) {
; #pragma unroll
;                     for (int bj = 0; bj < 2; ++bj)
; #pragma unroll
;                         for (int n = 0; n < 2; ++n) v[bj][n] = v[bj][n] * QS;
;                 } else if (sec == 3 || sec == 7) {
; #pragma unroll
;                     for (int bj = 0; bj < 2; ++bj)
; #pragma unroll
;                         for (int n = 0; n < 2; ++n)
; #pragma unroll
;                             for (int e = 0; e < 4; ++e) v[bj][n][e] = silu_f(v[bj][n][e]);
;                 }
;                 GAS f16* rowp = isqg ? QG + (size_t)dsec * QG_SEC + bl512((size_t)row, cs) : KV + (size_t)row * KVW + dsec * 512 + cs;
; #pragma unroll
;                 for (int bj = 0; bj < 2; ++bj) {
;                     u32x4 w; w.x = pkh(v[bj][0][0], v[bj][0][1]); w.y = pkh(v[bj][0][2], v[bj][0][3]); w.z = pkh(v[bj][1][0], v[bj][1][1]); w.w = pkh(v[bj][1][2], v[bj][1][3]);
;                     *(GAS u32x4*)(rowp + bjstep * bj) = w;
;                 }
	global_store_dwordx4 v133, v[160:163], s[6:7] sc0 sc1 nt
	v_cvt_pk_f16_f32 v164, v72, v73
	v_cvt_pk_f16_f32 v165, v74, v75
	v_cvt_pk_f16_f32 v166, v68, v69
	v_cvt_pk_f16_f32 v167, v70, v71
	global_store_dwordx4 v133, v[164:167], s[6:7] offset:2048 sc0 sc1 nt
	s_add_u32 s6, s4, 0x20000
	s_addc_u32 s7, s5, 0
	v_pk_mul_f32 v[64:65], v[64:65], v[142:143] op_sel_hi:[1,0]
	v_pk_mul_f32 v[66:67], v[66:67], v[142:143] op_sel_hi:[1,0]
	v_pk_mul_f32 v[60:61], v[60:61], v[142:143] op_sel_hi:[1,0]
	v_pk_mul_f32 v[62:63], v[62:63], v[142:143] op_sel_hi:[1,0]
	v_pk_mul_f32 v[32:33], v[32:33], v[142:143] op_sel_hi:[1,0]
	v_pk_mul_f32 v[34:35], v[34:35], v[142:143] op_sel_hi:[1,0]
	v_pk_mul_f32 v[28:29], v[28:29], v[142:143] op_sel_hi:[1,0]
	v_pk_mul_f32 v[30:31], v[30:31], v[142:143] op_sel_hi:[1,0]
	v_mul_f32_e32 v168, 0xbfb8aa3b, v64
	v_mul_f32_e32 v169, 0xbfb8aa3b, v65
	v_mul_f32_e32 v170, 0xbfb8aa3b, v66
	v_mul_f32_e32 v171, 0xbfb8aa3b, v67
	v_exp_f32_e32 v168, v168
	v_exp_f32_e32 v169, v169
	v_exp_f32_e32 v170, v170
	v_exp_f32_e32 v171, v171
	v_add_f32_e32 v168, 1.0, v168
	v_add_f32_e32 v169, 1.0, v169
	v_add_f32_e32 v170, 1.0, v170
	v_add_f32_e32 v171, 1.0, v171
	v_rcp_f32_e32 v168, v168
	v_rcp_f32_e32 v169, v169
	v_rcp_f32_e32 v170, v170
	v_rcp_f32_e32 v171, v171
	v_pk_mul_f32 v[64:65], v[64:65], v[168:169]
	v_pk_mul_f32 v[66:67], v[66:67], v[170:171]
	v_mul_f32_e32 v168, 0xbfb8aa3b, v60
	v_mul_f32_e32 v169, 0xbfb8aa3b, v61
	v_mul_f32_e32 v170, 0xbfb8aa3b, v62
	v_mul_f32_e32 v171, 0xbfb8aa3b, v63
	v_exp_f32_e32 v168, v168
	v_exp_f32_e32 v169, v169
	v_exp_f32_e32 v170, v170
	v_exp_f32_e32 v171, v171
	v_add_f32_e32 v168, 1.0, v168
	v_add_f32_e32 v169, 1.0, v169
	v_add_f32_e32 v170, 1.0, v170
	v_add_f32_e32 v171, 1.0, v171
	v_rcp_f32_e32 v168, v168
	v_rcp_f32_e32 v169, v169
	v_rcp_f32_e32 v170, v170
	v_rcp_f32_e32 v171, v171
	v_pk_mul_f32 v[60:61], v[60:61], v[168:169]
	v_pk_mul_f32 v[62:63], v[62:63], v[170:171]
	v_mul_f32_e32 v168, 0xbfb8aa3b, v32
	v_mul_f32_e32 v169, 0xbfb8aa3b, v33
	v_mul_f32_e32 v170, 0xbfb8aa3b, v34
	v_mul_f32_e32 v171, 0xbfb8aa3b, v35
	v_exp_f32_e32 v168, v168
	v_exp_f32_e32 v169, v169
	v_exp_f32_e32 v170, v170
	v_exp_f32_e32 v171, v171
	v_add_f32_e32 v168, 1.0, v168
	v_add_f32_e32 v169, 1.0, v169
	v_add_f32_e32 v170, 1.0, v170
	v_add_f32_e32 v171, 1.0, v171
	v_rcp_f32_e32 v168, v168
	v_rcp_f32_e32 v169, v169
	v_rcp_f32_e32 v170, v170
	v_rcp_f32_e32 v171, v171
	v_pk_mul_f32 v[32:33], v[32:33], v[168:169]
	v_pk_mul_f32 v[34:35], v[34:35], v[170:171]
	v_mul_f32_e32 v168, 0xbfb8aa3b, v28
	v_mul_f32_e32 v169, 0xbfb8aa3b, v29
	v_mul_f32_e32 v170, 0xbfb8aa3b, v30
	v_mul_f32_e32 v171, 0xbfb8aa3b, v31
	v_exp_f32_e32 v168, v168
	v_exp_f32_e32 v169, v169
	v_exp_f32_e32 v170, v170
	v_exp_f32_e32 v171, v171
	v_add_f32_e32 v168, 1.0, v168
	v_add_f32_e32 v169, 1.0, v169
	v_add_f32_e32 v170, 1.0, v170
	v_add_f32_e32 v171, 1.0, v171
	v_rcp_f32_e32 v168, v168
	v_rcp_f32_e32 v169, v169
	v_rcp_f32_e32 v170, v170
	v_rcp_f32_e32 v171, v171
	v_pk_mul_f32 v[28:29], v[28:29], v[168:169]
	v_pk_mul_f32 v[30:31], v[30:31], v[170:171]
	v_cvt_pk_f16_f32 v152, v64, v65
	v_cvt_pk_f16_f32 v153, v66, v67
	v_cvt_pk_f16_f32 v154, v60, v61
	v_cvt_pk_f16_f32 v155, v62, v63
	global_store_dwordx4 v133, v[152:155], s[6:7] sc0 sc1 nt
	v_cvt_pk_f16_f32 v156, v32, v33
	v_cvt_pk_f16_f32 v157, v34, v35
	v_cvt_pk_f16_f32 v158, v28, v29
	v_cvt_pk_f16_f32 v159, v30, v31
	global_store_dwordx4 v133, v[156:159], s[6:7] offset:2048 sc0 sc1 nt
	s_add_u32 s6, s4, 0x20100
	s_addc_u32 s7, s5, 0
	v_pk_mul_f32 v[56:57], v[56:57], v[144:145] op_sel_hi:[1,0]
	v_pk_mul_f32 v[58:59], v[58:59], v[144:145] op_sel_hi:[1,0]
	v_pk_mul_f32 v[52:53], v[52:53], v[144:145] op_sel_hi:[1,0]
	v_pk_mul_f32 v[54:55], v[54:55], v[144:145] op_sel_hi:[1,0]
	v_pk_mul_f32 v[24:25], v[24:25], v[144:145] op_sel_hi:[1,0]
	v_pk_mul_f32 v[26:27], v[26:27], v[144:145] op_sel_hi:[1,0]
	v_pk_mul_f32 v[20:21], v[20:21], v[144:145] op_sel_hi:[1,0]
	v_pk_mul_f32 v[22:23], v[22:23], v[144:145] op_sel_hi:[1,0]
	v_mul_f32_e32 v168, 0xbfb8aa3b, v56
	v_mul_f32_e32 v169, 0xbfb8aa3b, v57
	v_mul_f32_e32 v170, 0xbfb8aa3b, v58
	v_mul_f32_e32 v171, 0xbfb8aa3b, v59
	v_exp_f32_e32 v168, v168
	v_exp_f32_e32 v169, v169
	v_exp_f32_e32 v170, v170
	v_exp_f32_e32 v171, v171
	v_add_f32_e32 v168, 1.0, v168
	v_add_f32_e32 v169, 1.0, v169
	v_add_f32_e32 v170, 1.0, v170
	v_add_f32_e32 v171, 1.0, v171
	v_rcp_f32_e32 v168, v168
	v_rcp_f32_e32 v169, v169
	v_rcp_f32_e32 v170, v170
	v_rcp_f32_e32 v171, v171
	v_pk_mul_f32 v[56:57], v[56:57], v[168:169]
	v_pk_mul_f32 v[58:59], v[58:59], v[170:171]
	v_mul_f32_e32 v168, 0xbfb8aa3b, v52
	v_mul_f32_e32 v169, 0xbfb8aa3b, v53
	v_mul_f32_e32 v170, 0xbfb8aa3b, v54
	v_mul_f32_e32 v171, 0xbfb8aa3b, v55
	v_exp_f32_e32 v168, v168
	v_exp_f32_e32 v169, v169
	v_exp_f32_e32 v170, v170
	v_exp_f32_e32 v171, v171
	v_add_f32_e32 v168, 1.0, v168
	v_add_f32_e32 v169, 1.0, v169
	v_add_f32_e32 v170, 1.0, v170
	v_add_f32_e32 v171, 1.0, v171
	v_rcp_f32_e32 v168, v168
	v_rcp_f32_e32 v169, v169
	v_rcp_f32_e32 v170, v170
	v_rcp_f32_e32 v171, v171
	v_pk_mul_f32 v[52:53], v[52:53], v[168:169]
	v_pk_mul_f32 v[54:55], v[54:55], v[170:171]
	v_mul_f32_e32 v168, 0xbfb8aa3b, v24
	v_mul_f32_e32 v169, 0xbfb8aa3b, v25
	v_mul_f32_e32 v170, 0xbfb8aa3b, v26
	v_mul_f32_e32 v171, 0xbfb8aa3b, v27
	v_exp_f32_e32 v168, v168
	v_exp_f32_e32 v169, v169
	v_exp_f32_e32 v170, v170
	v_exp_f32_e32 v171, v171
	v_add_f32_e32 v168, 1.0, v168
	v_add_f32_e32 v169, 1.0, v169
	v_add_f32_e32 v170, 1.0, v170
	v_add_f32_e32 v171, 1.0, v171
	v_rcp_f32_e32 v168, v168
	v_rcp_f32_e32 v169, v169
	v_rcp_f32_e32 v170, v170
	v_rcp_f32_e32 v171, v171
; #define GAS __attribute__((address_space(1)))
; __host__ __device__ __forceinline__ size_t bl512(size_t row, int col) { return ((row >> 5) * 64 + (size_t)(col >> 3)) * 256 + (row & 31) * 8 + (col & 7); }
; __device__ __forceinline__ float silu_f(float v) { return v * __builtin_amdgcn_rcpf(1.0f + __builtin_amdgcn_exp2f(-v * LOG2E)); }
;     __device__ __forceinline__ void operator()(const f32x4 (&acc)[2][2][4][2], const Unit& u, int wr, int wc, int fr, int fq) const {
;     ...
;                 f32x4 v[2][2];
; #pragma unroll
;                 for (int bj = 0; bj < 2; ++bj)
; #pragma unroll
;                     for (int n = 0; n < 2; ++n) v[bj][n] = acc[ai][bj][m][n] * rs;
;                 if (sec == 4 || sec == 5) {
;                     float ss = 0.f;
; #pragma unroll
;                     for (int bj = 0; bj < 2; ++bj)
; #pragma unroll
;                         for (int n = 0; n < 2; ++n) { const f32x4 x = v[bj][n]; ss += (x[0] * x[0] + x[1] * x[1]) + (x[2] * x[2] + x[3] * x[3]); }
;                     ss = row4_sum(ss);
;                     float rn = __builtin_amdgcn_rsqf(ss * (1.0f / 64.0f) + RMS_EPS);
;                     if (sec == 4) rn *= QS;
; #pragma unroll
;                     for (int bj = 0; bj < 2; ++bj)
; #pragma unroll
;                         for (int n = 0; n < 2; ++n) v[bj][n] = v[bj][n] * rn * gain[bj][n];
;                 } else if (sec == 0) {
; #pragma unroll
;                     for (int bj = 0; bj < 2; ++bj)
; #pragma unroll
;                         for (int n = 0; n < 2; ++n) v[bj][n] = v[bj][n] * QS;
;                 } else if (sec == 3 || sec == 7) {
; #pragma unroll
;                     for (int bj = 0; bj < 2; ++bj)
; #pragma unroll
;                         for (int n = 0; n < 2; ++n)
; #pragma unroll
;                             for (int e = 0; e < 4; ++e) v[bj][n][e] = silu_f(v[bj][n][e]);
;                 }
;                 GAS f16* rowp = isqg ? QG + (size_t)dsec * QG_SEC + bl512((size_t)row, cs) : KV + (size_t)row * KVW + dsec * 512 + cs;
; #pragma unroll
;                 for (int bj = 0; bj < 2; ++bj) {
;                     u32x4 w; w.x = pkh(v[bj][0][0], v[bj][0][1]); w.y = pkh(v[bj][0][2], v[bj][0][3]); w.z = pkh(v[bj][1][0], v[bj][1][1]); w.w = pkh(v[bj][1][2], v[bj][1][3]);
;                     *(GAS u32x4*)(rowp + bjstep * bj) = w;
;                 }
	v_pk_mul_f32 v[24:25], v[24:25], v[168:169]
	v_pk_mul_f32 v[26:27], v[26:27], v[170:171]
	v_mul_f32_e32 v168, 0xbfb8aa3b, v20
	v_mul_f32_e32 v169, 0xbfb8aa3b, v21
	v_mul_f32_e32 v170, 0xbfb8aa3b, v22
	v_mul_f32_e32 v171, 0xbfb8aa3b, v23
	v_exp_f32_e32 v168, v168
	v_exp_f32_e32 v169, v169
	v_exp_f32_e32 v170, v170
	v_exp_f32_e32 v171, v171
	v_add_f32_e32 v168, 1.0, v168
	v_add_f32_e32 v169, 1.0, v169
	v_add_f32_e32 v170, 1.0, v170
	v_add_f32_e32 v171, 1.0, v171
	v_rcp_f32_e32 v168, v168
	v_rcp_f32_e32 v169, v169
	v_rcp_f32_e32 v170, v170
	v_rcp_f32_e32 v171, v171
	v_pk_mul_f32 v[20:21], v[20:21], v[168:169]
	v_pk_mul_f32 v[22:23], v[22:23], v[170:171]
	v_cvt_pk_f16_f32 v160, v56, v57
	v_cvt_pk_f16_f32 v161, v58, v59
	v_cvt_pk_f16_f32 v162, v52, v53
	v_cvt_pk_f16_f32 v163, v54, v55
	global_store_dwordx4 v133, v[160:163], s[6:7] sc0 sc1 nt
	v_cvt_pk_f16_f32 v164, v24, v25
	v_cvt_pk_f16_f32 v165, v26, v27
	v_cvt_pk_f16_f32 v166, v20, v21
	v_cvt_pk_f16_f32 v167, v22, v23
	global_store_dwordx4 v133, v[164:167], s[6:7] offset:2048 sc0 sc1 nt
	s_add_u32 s6, s4, 0x28000
	s_addc_u32 s7, s5, 0
	v_pk_mul_f32 v[48:49], v[48:49], v[146:147] op_sel_hi:[1,0]
	v_pk_mul_f32 v[50:51], v[50:51], v[146:147] op_sel_hi:[1,0]
	v_pk_mul_f32 v[44:45], v[44:45], v[146:147] op_sel_hi:[1,0]
	v_pk_mul_f32 v[46:47], v[46:47], v[146:147] op_sel_hi:[1,0]
	v_pk_mul_f32 v[16:17], v[16:17], v[146:147] op_sel_hi:[1,0]
	v_pk_mul_f32 v[18:19], v[18:19], v[146:147] op_sel_hi:[1,0]
	v_pk_mul_f32 v[12:13], v[12:13], v[146:147] op_sel_hi:[1,0]
	v_pk_mul_f32 v[14:15], v[14:15], v[146:147] op_sel_hi:[1,0]
	v_mul_f32_e32 v168, 0xbfb8aa3b, v48
	v_mul_f32_e32 v169, 0xbfb8aa3b, v49
	v_mul_f32_e32 v170, 0xbfb8aa3b, v50
	v_mul_f32_e32 v171, 0xbfb8aa3b, v51
	v_exp_f32_e32 v168, v168
	v_exp_f32_e32 v169, v169
	v_exp_f32_e32 v170, v170
	v_exp_f32_e32 v171, v171
	v_add_f32_e32 v168, 1.0, v168
	v_add_f32_e32 v169, 1.0, v169
	v_add_f32_e32 v170, 1.0, v170
	v_add_f32_e32 v171, 1.0, v171
	v_rcp_f32_e32 v168, v168
	v_rcp_f32_e32 v169, v169
	v_rcp_f32_e32 v170, v170
	v_rcp_f32_e32 v171, v171
	v_pk_mul_f32 v[48:49], v[48:49], v[168:169]
	v_pk_mul_f32 v[50:51], v[50:51], v[170:171]
	v_mul_f32_e32 v168, 0xbfb8aa3b, v44
	v_mul_f32_e32 v169, 0xbfb8aa3b, v45
	v_mul_f32_e32 v170, 0xbfb8aa3b, v46
	v_mul_f32_e32 v171, 0xbfb8aa3b, v47
	v_exp_f32_e32 v168, v168
	v_exp_f32_e32 v169, v169
	v_exp_f32_e32 v170, v170
	v_exp_f32_e32 v171, v171
	v_add_f32_e32 v168, 1.0, v168
	v_add_f32_e32 v169, 1.0, v169
	v_add_f32_e32 v170, 1.0, v170
	v_add_f32_e32 v171, 1.0, v171
	v_rcp_f32_e32 v168, v168
	v_rcp_f32_e32 v169, v169
	v_rcp_f32_e32 v170, v170
	v_rcp_f32_e32 v171, v171
	v_pk_mul_f32 v[44:45], v[44:45], v[168:169]
	v_pk_mul_f32 v[46:47], v[46:47], v[170:171]
	v_mul_f32_e32 v168, 0xbfb8aa3b, v16
	v_mul_f32_e32 v169, 0xbfb8aa3b, v17
	v_mul_f32_e32 v170, 0xbfb8aa3b, v18
	v_mul_f32_e32 v171, 0xbfb8aa3b, v19
	v_exp_f32_e32 v168, v168
	v_exp_f32_e32 v169, v169
	v_exp_f32_e32 v170, v170
	v_exp_f32_e32 v171, v171
	v_add_f32_e32 v168, 1.0, v168
	v_add_f32_e32 v169, 1.0, v169
	v_add_f32_e32 v170, 1.0, v170
	v_add_f32_e32 v171, 1.0, v171
	v_rcp_f32_e32 v168, v168
	v_rcp_f32_e32 v169, v169
	v_rcp_f32_e32 v170, v170
	v_rcp_f32_e32 v171, v171
	v_pk_mul_f32 v[16:17], v[16:17], v[168:169]
	v_pk_mul_f32 v[18:19], v[18:19], v[170:171]
	v_mul_f32_e32 v168, 0xbfb8aa3b, v12
	v_mul_f32_e32 v169, 0xbfb8aa3b, v13
	v_mul_f32_e32 v170, 0xbfb8aa3b, v14
	v_mul_f32_e32 v171, 0xbfb8aa3b, v15
	v_exp_f32_e32 v168, v168
	v_exp_f32_e32 v169, v169
	v_exp_f32_e32 v170, v170
	v_exp_f32_e32 v171, v171
	v_add_f32_e32 v168, 1.0, v168
	v_add_f32_e32 v169, 1.0, v169
	v_add_f32_e32 v170, 1.0, v170
	v_add_f32_e32 v171, 1.0, v171
	v_rcp_f32_e32 v168, v168
	v_rcp_f32_e32 v169, v169
	v_rcp_f32_e32 v170, v170
	v_rcp_f32_e32 v171, v171
	v_pk_mul_f32 v[12:13], v[12:13], v[168:169]
	v_pk_mul_f32 v[14:15], v[14:15], v[170:171]
	v_cvt_pk_f16_f32 v152, v48, v49
	v_cvt_pk_f16_f32 v153, v50, v51
	v_cvt_pk_f16_f32 v154, v44, v45
	v_cvt_pk_f16_f32 v155, v46, v47
	global_store_dwordx4 v133, v[152:155], s[6:7] sc0 sc1 nt
	v_cvt_pk_f16_f32 v156, v16, v17
	v_cvt_pk_f16_f32 v157, v18, v19
	v_cvt_pk_f16_f32 v158, v12, v13
	v_cvt_pk_f16_f32 v159, v14, v15
	global_store_dwordx4 v133, v[156:159], s[6:7] offset:2048 sc0 sc1 nt
	s_add_u32 s6, s4, 0x28100
	s_addc_u32 s7, s5, 0
	v_pk_mul_f32 v[40:41], v[40:41], v[148:149] op_sel_hi:[1,0]
	v_pk_mul_f32 v[42:43], v[42:43], v[148:149] op_sel_hi:[1,0]
	v_pk_mul_f32 v[36:37], v[36:37], v[148:149] op_sel_hi:[1,0]
	v_pk_mul_f32 v[38:39], v[38:39], v[148:149] op_sel_hi:[1,0]
	v_pk_mul_f32 v[8:9], v[8:9], v[148:149] op_sel_hi:[1,0]
	v_pk_mul_f32 v[10:11], v[10:11], v[148:149] op_sel_hi:[1,0]
	v_pk_mul_f32 v[4:5], v[4:5], v[148:149] op_sel_hi:[1,0]
	v_pk_mul_f32 v[6:7], v[6:7], v[148:149] op_sel_hi:[1,0]
	v_mul_f32_e32 v168, 0xbfb8aa3b, v40
	v_mul_f32_e32 v169, 0xbfb8aa3b, v41
	v_mul_f32_e32 v170, 0xbfb8aa3b, v42
	v_mul_f32_e32 v171, 0xbfb8aa3b, v43
	v_exp_f32_e32 v168, v168
	v_exp_f32_e32 v169, v169
	v_exp_f32_e32 v170, v170
	v_exp_f32_e32 v171, v171
	v_add_f32_e32 v168, 1.0, v168
	v_add_f32_e32 v169, 1.0, v169
	v_add_f32_e32 v170, 1.0, v170
	v_add_f32_e32 v171, 1.0, v171
	v_rcp_f32_e32 v168, v168
	v_rcp_f32_e32 v169, v169
	v_rcp_f32_e32 v170, v170
	v_rcp_f32_e32 v171, v171
	v_pk_mul_f32 v[40:41], v[40:41], v[168:169]
	v_pk_mul_f32 v[42:43], v[42:43], v[170:171]
	v_mul_f32_e32 v168, 0xbfb8aa3b, v36
	v_mul_f32_e32 v169, 0xbfb8aa3b, v37
	v_mul_f32_e32 v170, 0xbfb8aa3b, v38
	v_mul_f32_e32 v171, 0xbfb8aa3b, v39
	v_exp_f32_e32 v168, v168
	v_exp_f32_e32 v169, v169
	v_exp_f32_e32 v170, v170
	v_exp_f32_e32 v171, v171
	v_add_f32_e32 v168, 1.0, v168
;     __device__ __forceinline__ void operator()(const f32x4 (&acc)[2][2][4][2], const Unit& u, int wr, int wc, int fr, int fq) const {
;     ...
;         if (sec == 4 || sec == 5) {
;             const GAS float* g = (sec == 4) ? gq : gk;
; #pragma unroll
;             for (int bj = 0; bj < 2; ++bj)
; #pragma unroll
;                 for (int n = 0; n < 2; ++n) gain[bj][n] = *(const GAS f32x4*)(g + 32 * bj + 8 * fq + 4 * n);
;         }
;         const LAS int* tags = (const LAS int*)(rsc + 2048);
;         const int slot = (tags[0] == u.pm) ? 0 : (tags[1] == u.pm) ? 1 : -1;
;         const LAS float* rtab = (const LAS float*)rsc + (slot > 0 ? 256 : 0) + wr * 64 + fr;
; #pragma unroll
;         for (int ai = 0; ai < 2; ++ai)
; #pragma unroll
;             for (int m = 0; m < 4; ++m) {
;                 const int row = row0 + ai * HALF + m * 16;
;                 float rs;
;                 if (slot >= 0) rs = rtab[ai * HALF + m * 16];
;                 else {
;                     const f32x4 pv = *(const GAS f32x4*)(part + (size_t)row * 16 + fq * 4);
;                     float s = (pv[0] + pv[1]) + (pv[2] + pv[3]);
;                     s = row4_sum(s);
;                     rs = __builtin_amdgcn_rsqf(s * (1.0f / DM) + RMS_EPS);
;                 }
;                 f32x4 v[2][2];
; #pragma unroll
;                 for (int bj = 0; bj < 2; ++bj)
; #pragma unroll
;                     for (int n = 0; n < 2; ++n) v[bj][n] = acc[ai][bj][m][n] * rs;
;                 if (sec == 4 || sec == 5) {
;                     float ss = 0.f;
; #pragma unroll
;                     for (int bj = 0; bj < 2; ++bj)
; #pragma unroll
;                         for (int n = 0; n < 2; ++n) { const f32x4 x = v[bj][n]; ss += (x[0] * x[0] + x[1] * x[1]) + (x[2] * x[2] + x[3] * x[3]); }
;                     ss = row4_sum(ss);
;                     float rn = __builtin_amdgcn_rsqf(ss * (1.0f / 64.0f) + RMS_EPS);
;                     if (sec == 4) rn *= QS;
; #pragma unroll
;                     for (int bj = 0; bj < 2; ++bj)
; #pragma unroll
;                         for (int n = 0; n < 2; ++n) v[bj][n] = v[bj][n] * rn * gain[bj][n];
;                 } else if (sec == 0) {
; #pragma unroll
;                     for (int bj = 0; bj < 2; ++bj)
; #pragma unroll
;                         for (int n = 0; n < 2; ++n) v[bj][n] = v[bj][n] * QS;
;                 } else if (sec == 3 || sec == 7) {
	v_add_f32_e32 v169, 1.0, v169
	v_add_f32_e32 v170, 1.0, v170
	v_add_f32_e32 v171, 1.0, v171
	v_rcp_f32_e32 v168, v168
	v_rcp_f32_e32 v169, v169
	v_rcp_f32_e32 v170, v170
	v_rcp_f32_e32 v171, v171
	v_pk_mul_f32 v[36:37], v[36:37], v[168:169]
	v_pk_mul_f32 v[38:39], v[38:39], v[170:171]
	v_mul_f32_e32 v168, 0xbfb8aa3b, v8
	v_mul_f32_e32 v169, 0xbfb8aa3b, v9
	v_mul_f32_e32 v170, 0xbfb8aa3b, v10
	v_mul_f32_e32 v171, 0xbfb8aa3b, v11
	v_exp_f32_e32 v168, v168
	v_exp_f32_e32 v169, v169
	v_exp_f32_e32 v170, v170
	v_exp_f32_e32 v171, v171
	v_add_f32_e32 v168, 1.0, v168
	v_add_f32_e32 v169, 1.0, v169
	v_add_f32_e32 v170, 1.0, v170
	v_add_f32_e32 v171, 1.0, v171
	v_rcp_f32_e32 v168, v168
	v_rcp_f32_e32 v169, v169
	v_rcp_f32_e32 v170, v170
	v_rcp_f32_e32 v171, v171
	v_pk_mul_f32 v[8:9], v[8:9], v[168:169]
	v_pk_mul_f32 v[10:11], v[10:11], v[170:171]
	v_mul_f32_e32 v168, 0xbfb8aa3b, v4
	v_mul_f32_e32 v169, 0xbfb8aa3b, v5
	v_mul_f32_e32 v170, 0xbfb8aa3b, v6
	v_mul_f32_e32 v171, 0xbfb8aa3b, v7
	v_exp_f32_e32 v168, v168
	v_exp_f32_e32 v169, v169
	v_exp_f32_e32 v170, v170
	v_exp_f32_e32 v171, v171
	v_add_f32_e32 v168, 1.0, v168
	v_add_f32_e32 v169, 1.0, v169
	v_add_f32_e32 v170, 1.0, v170
	v_add_f32_e32 v171, 1.0, v171
	v_rcp_f32_e32 v168, v168
	v_rcp_f32_e32 v169, v169
	v_rcp_f32_e32 v170, v170
	v_rcp_f32_e32 v171, v171
	v_pk_mul_f32 v[4:5], v[4:5], v[168:169]
	v_pk_mul_f32 v[6:7], v[6:7], v[170:171]
	v_cvt_pk_f16_f32 v160, v40, v41
	v_cvt_pk_f16_f32 v161, v42, v43
	v_cvt_pk_f16_f32 v162, v36, v37
	v_cvt_pk_f16_f32 v163, v38, v39
	global_store_dwordx4 v133, v[160:163], s[6:7] sc0 sc1 nt
	v_cvt_pk_f16_f32 v164, v8, v9
	v_cvt_pk_f16_f32 v165, v10, v11
	v_cvt_pk_f16_f32 v166, v4, v5
	v_cvt_pk_f16_f32 v167, v6, v7
	global_store_dwordx4 v133, v[164:167], s[6:7] offset:2048 sc0 sc1 nt
	s_branch .Lepi_done_g1
.Lepi_qn:
	s_and_b32 s0, s70, 1
	s_lshl_b32 s0, s0, 10
	v_add_u32_e32 v132, s0, v219
	ds_read_b32 v134, v132
	ds_read_b32 v136, v132 offset:64
	ds_read_b32 v138, v132 offset:128
	ds_read_b32 v140, v132 offset:192
	ds_read_b32 v142, v132 offset:512
	ds_read_b32 v144, v132 offset:576
	ds_read_b32 v146, v132 offset:640
	ds_read_b32 v148, v132 offset:704
	s_lshr_b32 s0, s69, 2
	s_and_b32 s1, s69, 1
	v_lshrrev_b32_e32 v2, 6, v187
	v_lshrrev_b32_e32 v133, 3, v220
	v_lshl_add_u32 v133, v2, 7, v133
	v_and_b32_e32 v2, 15, v187
	v_lshlrev_b32_e32 v133, 8, v133
	v_lshl_add_u32 v133, v2, 3, v133
	v_lshlrev_b32_e32 v133, 1, v133
	s_lshl_b32 s0, s0, 25
	s_lshl_b32 s1, s1, 14
	s_add_u32 s0, s0, s1
	s_lshl_b32 s1, s68, 18
	s_add_u32 s0, s0, s1
	s_add_u32 s4, s82, s0
	s_addc_u32 s5, s83, 0
	v_readlane_b32 s10, v252, 17
	v_readlane_b32 s11, v252, 18
	s_lshl_b32 s0, s22, 2
	s_nop 0
	s_add_u32 s10, s10, s0
	s_addc_u32 s11, s11, 0
	s_nop 3
	global_load_dwordx4 v[176:179], v222, s[10:11]
	global_load_dwordx4 v[206:209], v222, s[10:11] offset:16
	global_load_dwordx4 v[224:227], v222, s[10:11] offset:128
	global_load_dwordx4 v[228:231], v222, s[10:11] offset:144
	s_waitcnt vmcnt(0)
	s_waitcnt lgkmcnt(0)
	s_mov_b32 s6, s4
	s_mov_b32 s7, s5
	v_pk_mul_f32 v[128:129], v[128:129], v[134:135] op_sel_hi:[1,0]
	v_pk_mul_f32 v[130:131], v[130:131], v[134:135] op_sel_hi:[1,0]
	v_pk_mul_f32 v[124:125], v[124:125], v[134:135] op_sel_hi:[1,0]
	v_pk_mul_f32 v[126:127], v[126:127], v[134:135] op_sel_hi:[1,0]
	v_pk_mul_f32 v[96:97], v[96:97], v[134:135] op_sel_hi:[1,0]
	v_pk_mul_f32 v[98:99], v[98:99], v[134:135] op_sel_hi:[1,0]
	v_pk_mul_f32 v[92:93], v[92:93], v[134:135] op_sel_hi:[1,0]
	v_pk_mul_f32 v[94:95], v[94:95], v[134:135] op_sel_hi:[1,0]
	v_mul_f32_e32 v2, v128, v128
	v_mul_f32_e32 v150, v129, v129
	v_fmac_f32_e32 v2, v130, v130
	v_fmac_f32_e32 v150, v131, v131
	v_fmac_f32_e32 v2, v124, v124
	v_fmac_f32_e32 v150, v125, v125
	v_fmac_f32_e32 v2, v126, v126
	v_fmac_f32_e32 v150, v127, v127
	v_fmac_f32_e32 v2, v96, v96
	v_fmac_f32_e32 v150, v97, v97
	v_fmac_f32_e32 v2, v98, v98
	v_fmac_f32_e32 v150, v99, v99
	v_fmac_f32_e32 v2, v92, v92
	v_fmac_f32_e32 v150, v93, v93
	v_fmac_f32_e32 v2, v94, v94
	v_fmac_f32_e32 v150, v95, v95
	v_add_f32_e32 v2, v2, v150
	v_mov_b32_e32 v150, v2
	s_nop 1
	v_permlane16_swap_b32_e32 v2, v150
	v_add_f32_e32 v2, v2, v150
	v_mov_b32_e32 v150, v2
	s_nop 1
	v_permlane32_swap_b32_e32 v2, v150
	v_add_f32_e32 v2, v2, v150
	v_fmamk_f32 v2, v2, 0x3c800000, v211
	v_rsq_f32_e32 v2, v2
	s_nop 0
	v_mul_f32_e32 v2, s78, v2
	v_pk_mul_f32 v[128:129], v[128:129], v[2:3] op_sel_hi:[1,0]
	v_pk_mul_f32 v[130:131], v[130:131], v[2:3] op_sel_hi:[1,0]
	v_pk_mul_f32 v[124:125], v[124:125], v[2:3] op_sel_hi:[1,0]
	v_pk_mul_f32 v[126:127], v[126:127], v[2:3] op_sel_hi:[1,0]
	v_pk_mul_f32 v[96:97], v[96:97], v[2:3] op_sel_hi:[1,0]
	v_pk_mul_f32 v[98:99], v[98:99], v[2:3] op_sel_hi:[1,0]
	v_pk_mul_f32 v[92:93], v[92:93], v[2:3] op_sel_hi:[1,0]
	v_pk_mul_f32 v[94:95], v[94:95], v[2:3] op_sel_hi:[1,0]
	v_pk_mul_f32 v[128:129], v[128:129], v[176:177]
	v_pk_mul_f32 v[130:131], v[130:131], v[178:179]
	v_pk_mul_f32 v[124:125], v[124:125], v[206:207]
	v_pk_mul_f32 v[126:127], v[126:127], v[208:209]
	v_pk_mul_f32 v[96:97], v[96:97], v[224:225]
	v_pk_mul_f32 v[98:99], v[98:99], v[226:227]
	v_pk_mul_f32 v[92:93], v[92:93], v[228:229]
	v_pk_mul_f32 v[94:95], v[94:95], v[230:231]
	v_cvt_pk_f16_f32 v152, v128, v129
	v_cvt_pk_f16_f32 v153, v130, v131
	v_cvt_pk_f16_f32 v154, v124, v125
	v_cvt_pk_f16_f32 v155, v126, v127
	global_store_dwordx4 v133, v[152:155], s[6:7] sc0 sc1 nt
	v_cvt_pk_f16_f32 v156, v96, v97
	v_cvt_pk_f16_f32 v157, v98, v99
	v_cvt_pk_f16_f32 v158, v92, v93
	v_cvt_pk_f16_f32 v159, v94, v95
	global_store_dwordx4 v133, v[156:159], s[6:7] offset:2048 sc0 sc1 nt
	s_add_u32 s6, s4, 0x100
; __device__ __forceinline__ float row4_sum(float s) {
;     { const auto r = __builtin_amdgcn_permlane16_swap(__float_as_uint(s), __float_as_uint(s), false, false); s = __uint_as_float(r[0]) + __uint_as_float(r[1]); }
;     { const auto r = __builtin_amdgcn_permlane32_swap(__float_as_uint(s), __float_as_uint(s), false, false); s = __uint_as_float(r[0]) + __uint_as_float(r[1]); }
;     __device__ __forceinline__ void operator()(const f32x4 (&acc)[2][2][4][2], const Unit& u, int wr, int wc, int fr, int fq) const {
;     ...
;                 f32x4 v[2][2];
; #pragma unroll
;                 for (int bj = 0; bj < 2; ++bj)
; #pragma unroll
;                     for (int n = 0; n < 2; ++n) v[bj][n] = acc[ai][bj][m][n] * rs;
;                 if (sec == 4 || sec == 5) {
;                     float ss = 0.f;
; #pragma unroll
;                     for (int bj = 0; bj < 2; ++bj)
; #pragma unroll
;                         for (int n = 0; n < 2; ++n) { const f32x4 x = v[bj][n]; ss += (x[0] * x[0] + x[1] * x[1]) + (x[2] * x[2] + x[3] * x[3]); }
;                     ss = row4_sum(ss);
;                     float rn = __builtin_amdgcn_rsqf(ss * (1.0f / 64.0f) + RMS_EPS);
;                     if (sec == 4) rn *= QS;
; #pragma unroll
;                     for (int bj = 0; bj < 2; ++bj)
; #pragma unroll
;                         for (int n = 0; n < 2; ++n) v[bj][n] = v[bj][n] * rn * gain[bj][n];
;                 } else if (sec == 0) {
; #pragma unroll
;                     for (int bj = 0; bj < 2; ++bj)
; #pragma unroll
;                         for (int n = 0; n < 2; ++n) v[bj][n] = v[bj][n] * QS;
;                 } else if (sec == 3 || sec == 7) {
; #pragma unroll
;                     for (int bj = 0; bj < 2; ++bj)
; #pragma unroll
;                         for (int n = 0; n < 2; ++n)
; #pragma unroll
;                             for (int e = 0; e < 4; ++e) v[bj][n][e] = silu_f(v[bj][n][e]);
;                 }
;                 GAS f16* rowp = isqg ? QG + (size_t)dsec * QG_SEC + bl512((size_t)row, cs) : KV + (size_t)row * KVW + dsec * 512 + cs;
; #pragma unroll
;                 for (int bj = 0; bj < 2; ++bj) {
;                     u32x4 w; w.x = pkh(v[bj][0][0], v[bj][0][1]); w.y = pkh(v[bj][0][2], v[bj][0][3]); w.z = pkh(v[bj][1][0], v[bj][1][1]); w.w = pkh(v[bj][1][2], v[bj][1][3]);
;                     *(GAS u32x4*)(rowp + bjstep * bj) = w;
;                 }
	s_addc_u32 s7, s5, 0
	v_pk_mul_f32 v[120:121], v[120:121], v[136:137] op_sel_hi:[1,0]
	v_pk_mul_f32 v[122:123], v[122:123], v[136:137] op_sel_hi:[1,0]
	v_pk_mul_f32 v[116:117], v[116:117], v[136:137] op_sel_hi:[1,0]
	v_pk_mul_f32 v[118:119], v[118:119], v[136:137] op_sel_hi:[1,0]
	v_pk_mul_f32 v[88:89], v[88:89], v[136:137] op_sel_hi:[1,0]
	v_pk_mul_f32 v[90:91], v[90:91], v[136:137] op_sel_hi:[1,0]
	v_pk_mul_f32 v[84:85], v[84:85], v[136:137] op_sel_hi:[1,0]
	v_pk_mul_f32 v[86:87], v[86:87], v[136:137] op_sel_hi:[1,0]
	v_mul_f32_e32 v2, v120, v120
	v_mul_f32_e32 v150, v121, v121
	v_fmac_f32_e32 v2, v122, v122
	v_fmac_f32_e32 v150, v123, v123
	v_fmac_f32_e32 v2, v116, v116
	v_fmac_f32_e32 v150, v117, v117
	v_fmac_f32_e32 v2, v118, v118
	v_fmac_f32_e32 v150, v119, v119
	v_fmac_f32_e32 v2, v88, v88
	v_fmac_f32_e32 v150, v89, v89
	v_fmac_f32_e32 v2, v90, v90
	v_fmac_f32_e32 v150, v91, v91
	v_fmac_f32_e32 v2, v84, v84
	v_fmac_f32_e32 v150, v85, v85
	v_fmac_f32_e32 v2, v86, v86
	v_fmac_f32_e32 v150, v87, v87
	v_add_f32_e32 v2, v2, v150
	v_mov_b32_e32 v150, v2
	s_nop 1
	v_permlane16_swap_b32_e32 v2, v150
	v_add_f32_e32 v2, v2, v150
	v_mov_b32_e32 v150, v2
	s_nop 1
	v_permlane32_swap_b32_e32 v2, v150
	v_add_f32_e32 v2, v2, v150
	v_fmamk_f32 v2, v2, 0x3c800000, v211
	v_rsq_f32_e32 v2, v2
	s_nop 0
	v_mul_f32_e32 v2, s78, v2
	v_pk_mul_f32 v[120:121], v[120:121], v[2:3] op_sel_hi:[1,0]
	v_pk_mul_f32 v[122:123], v[122:123], v[2:3] op_sel_hi:[1,0]
	v_pk_mul_f32 v[116:117], v[116:117], v[2:3] op_sel_hi:[1,0]
	v_pk_mul_f32 v[118:119], v[118:119], v[2:3] op_sel_hi:[1,0]
	v_pk_mul_f32 v[88:89], v[88:89], v[2:3] op_sel_hi:[1,0]
	v_pk_mul_f32 v[90:91], v[90:91], v[2:3] op_sel_hi:[1,0]
	v_pk_mul_f32 v[84:85], v[84:85], v[2:3] op_sel_hi:[1,0]
	v_pk_mul_f32 v[86:87], v[86:87], v[2:3] op_sel_hi:[1,0]
	v_pk_mul_f32 v[120:121], v[120:121], v[176:177]
	v_pk_mul_f32 v[122:123], v[122:123], v[178:179]
	v_pk_mul_f32 v[116:117], v[116:117], v[206:207]
	v_pk_mul_f32 v[118:119], v[118:119], v[208:209]
	v_pk_mul_f32 v[88:89], v[88:89], v[224:225]
	v_pk_mul_f32 v[90:91], v[90:91], v[226:227]
	v_pk_mul_f32 v[84:85], v[84:85], v[228:229]
	v_pk_mul_f32 v[86:87], v[86:87], v[230:231]
	v_cvt_pk_f16_f32 v160, v120, v121
	v_cvt_pk_f16_f32 v161, v122, v123
	v_cvt_pk_f16_f32 v162, v116, v117
	v_cvt_pk_f16_f32 v163, v118, v119
	global_store_dwordx4 v133, v[160:163], s[6:7] sc0 sc1 nt
	v_cvt_pk_f16_f32 v164, v88, v89
	v_cvt_pk_f16_f32 v165, v90, v91
	v_cvt_pk_f16_f32 v166, v84, v85
	v_cvt_pk_f16_f32 v167, v86, v87
	global_store_dwordx4 v133, v[164:167], s[6:7] offset:2048 sc0 sc1 nt
	s_add_u32 s6, s4, 0x8000
	s_addc_u32 s7, s5, 0
	v_pk_mul_f32 v[112:113], v[112:113], v[138:139] op_sel_hi:[1,0]
	v_pk_mul_f32 v[114:115], v[114:115], v[138:139] op_sel_hi:[1,0]
	v_pk_mul_f32 v[108:109], v[108:109], v[138:139] op_sel_hi:[1,0]
	v_pk_mul_f32 v[110:111], v[110:111], v[138:139] op_sel_hi:[1,0]
	v_pk_mul_f32 v[80:81], v[80:81], v[138:139] op_sel_hi:[1,0]
	v_pk_mul_f32 v[82:83], v[82:83], v[138:139] op_sel_hi:[1,0]
	v_pk_mul_f32 v[76:77], v[76:77], v[138:139] op_sel_hi:[1,0]
	v_pk_mul_f32 v[78:79], v[78:79], v[138:139] op_sel_hi:[1,0]
	v_mul_f32_e32 v2, v112, v112
	v_mul_f32_e32 v150, v113, v113
	v_fmac_f32_e32 v2, v114, v114
	v_fmac_f32_e32 v150, v115, v115
	v_fmac_f32_e32 v2, v108, v108
	v_fmac_f32_e32 v150, v109, v109
	v_fmac_f32_e32 v2, v110, v110
	v_fmac_f32_e32 v150, v111, v111
	v_fmac_f32_e32 v2, v80, v80
	v_fmac_f32_e32 v150, v81, v81
	v_fmac_f32_e32 v2, v82, v82
	v_fmac_f32_e32 v150, v83, v83
	v_fmac_f32_e32 v2, v76, v76
	v_fmac_f32_e32 v150, v77, v77
	v_fmac_f32_e32 v2, v78, v78
	v_fmac_f32_e32 v150, v79, v79
	v_add_f32_e32 v2, v2, v150
	v_mov_b32_e32 v150, v2
	s_nop 1
	v_permlane16_swap_b32_e32 v2, v150
	v_add_f32_e32 v2, v2, v150
	v_mov_b32_e32 v150, v2
	s_nop 1
	v_permlane32_swap_b32_e32 v2, v150
	v_add_f32_e32 v2, v2, v150
	v_fmamk_f32 v2, v2, 0x3c800000, v211
	v_rsq_f32_e32 v2, v2
	s_nop 0
	v_mul_f32_e32 v2, s78, v2
	v_pk_mul_f32 v[112:113], v[112:113], v[2:3] op_sel_hi:[1,0]
	v_pk_mul_f32 v[114:115], v[114:115], v[2:3] op_sel_hi:[1,0]
	v_pk_mul_f32 v[108:109], v[108:109], v[2:3] op_sel_hi:[1,0]
	v_pk_mul_f32 v[110:111], v[110:111], v[2:3] op_sel_hi:[1,0]
	v_pk_mul_f32 v[80:81], v[80:81], v[2:3] op_sel_hi:[1,0]
	v_pk_mul_f32 v[82:83], v[82:83], v[2:3] op_sel_hi:[1,0]
	v_pk_mul_f32 v[76:77], v[76:77], v[2:3] op_sel_hi:[1,0]
	v_pk_mul_f32 v[78:79], v[78:79], v[2:3] op_sel_hi:[1,0]
	v_pk_mul_f32 v[112:113], v[112:113], v[176:177]
	v_pk_mul_f32 v[114:115], v[114:115], v[178:179]
	v_pk_mul_f32 v[108:109], v[108:109], v[206:207]
	v_pk_mul_f32 v[110:111], v[110:111], v[208:209]
	v_pk_mul_f32 v[80:81], v[80:81], v[224:225]
	v_pk_mul_f32 v[82:83], v[82:83], v[226:227]
	v_pk_mul_f32 v[76:77], v[76:77], v[228:229]
	v_pk_mul_f32 v[78:79], v[78:79], v[230:231]
	v_cvt_pk_f16_f32 v152, v112, v113
	v_cvt_pk_f16_f32 v153, v114, v115
	v_cvt_pk_f16_f32 v154, v108, v109
	v_cvt_pk_f16_f32 v155, v110, v111
	global_store_dwordx4 v133, v[152:155], s[6:7] sc0 sc1 nt
	v_cvt_pk_f16_f32 v156, v80, v81
	v_cvt_pk_f16_f32 v157, v82, v83
	v_cvt_pk_f16_f32 v158, v76, v77
	v_cvt_pk_f16_f32 v159, v78, v79
	global_store_dwordx4 v133, v[156:159], s[6:7] offset:2048 sc0 sc1 nt
	s_add_u32 s6, s4, 0x8100
	s_addc_u32 s7, s5, 0
	v_pk_mul_f32 v[104:105], v[104:105], v[140:141] op_sel_hi:[1,0]
	v_pk_mul_f32 v[106:107], v[106:107], v[140:141] op_sel_hi:[1,0]
	v_pk_mul_f32 v[100:101], v[100:101], v[140:141] op_sel_hi:[1,0]
	v_pk_mul_f32 v[102:103], v[102:103], v[140:141] op_sel_hi:[1,0]
	v_pk_mul_f32 v[72:73], v[72:73], v[140:141] op_sel_hi:[1,0]
	v_pk_mul_f32 v[74:75], v[74:75], v[140:141] op_sel_hi:[1,0]
; __device__ __forceinline__ float row4_sum(float s) {
;     { const auto r = __builtin_amdgcn_permlane16_swap(__float_as_uint(s), __float_as_uint(s), false, false); s = __uint_as_float(r[0]) + __uint_as_float(r[1]); }
;     { const auto r = __builtin_amdgcn_permlane32_swap(__float_as_uint(s), __float_as_uint(s), false, false); s = __uint_as_float(r[0]) + __uint_as_float(r[1]); }
;     __device__ __forceinline__ void operator()(const f32x4 (&acc)[2][2][4][2], const Unit& u, int wr, int wc, int fr, int fq) const {
;     ...
;                 f32x4 v[2][2];
; #pragma unroll
;                 for (int bj = 0; bj < 2; ++bj)
; #pragma unroll
;                     for (int n = 0; n < 2; ++n) v[bj][n] = acc[ai][bj][m][n] * rs;
;                 if (sec == 4 || sec == 5) {
;                     float ss = 0.f;
; #pragma unroll
;                     for (int bj = 0; bj < 2; ++bj)
; #pragma unroll
;                         for (int n = 0; n < 2; ++n) { const f32x4 x = v[bj][n]; ss += (x[0] * x[0] + x[1] * x[1]) + (x[2] * x[2] + x[3] * x[3]); }
;                     ss = row4_sum(ss);
;                     float rn = __builtin_amdgcn_rsqf(ss * (1.0f / 64.0f) + RMS_EPS);
;                     if (sec == 4) rn *= QS;
; #pragma unroll
;                     for (int bj = 0; bj < 2; ++bj)
; #pragma unroll
;                         for (int n = 0; n < 2; ++n) v[bj][n] = v[bj][n] * rn * gain[bj][n];
;                 } else if (sec == 0) {
; #pragma unroll
;                     for (int bj = 0; bj < 2; ++bj)
; #pragma unroll
;                         for (int n = 0; n < 2; ++n) v[bj][n] = v[bj][n] * QS;
;                 } else if (sec == 3 || sec == 7) {
; #pragma unroll
;                     for (int bj = 0; bj < 2; ++bj)
; #pragma unroll
;                         for (int n = 0; n < 2; ++n)
; #pragma unroll
;                             for (int e = 0; e < 4; ++e) v[bj][n][e] = silu_f(v[bj][n][e]);
;                 }
;                 GAS f16* rowp = isqg ? QG + (size_t)dsec * QG_SEC + bl512((size_t)row, cs) : KV + (size_t)row * KVW + dsec * 512 + cs;
; #pragma unroll
;                 for (int bj = 0; bj < 2; ++bj) {
;                     u32x4 w; w.x = pkh(v[bj][0][0], v[bj][0][1]); w.y = pkh(v[bj][0][2], v[bj][0][3]); w.z = pkh(v[bj][1][0], v[bj][1][1]); w.w = pkh(v[bj][1][2], v[bj][1][3]);
;                     *(GAS u32x4*)(rowp + bjstep * bj) = w;
;                 }
	v_pk_mul_f32 v[68:69], v[68:69], v[140:141] op_sel_hi:[1,0]
	v_pk_mul_f32 v[70:71], v[70:71], v[140:141] op_sel_hi:[1,0]
	v_mul_f32_e32 v2, v104, v104
	v_mul_f32_e32 v150, v105, v105
	v_fmac_f32_e32 v2, v106, v106
	v_fmac_f32_e32 v150, v107, v107
	v_fmac_f32_e32 v2, v100, v100
	v_fmac_f32_e32 v150, v101, v101
	v_fmac_f32_e32 v2, v102, v102
	v_fmac_f32_e32 v150, v103, v103
	v_fmac_f32_e32 v2, v72, v72
	v_fmac_f32_e32 v150, v73, v73
	v_fmac_f32_e32 v2, v74, v74
	v_fmac_f32_e32 v150, v75, v75
	v_fmac_f32_e32 v2, v68, v68
	v_fmac_f32_e32 v150, v69, v69
	v_fmac_f32_e32 v2, v70, v70
	v_fmac_f32_e32 v150, v71, v71
	v_add_f32_e32 v2, v2, v150
	v_mov_b32_e32 v150, v2
	s_nop 1
	v_permlane16_swap_b32_e32 v2, v150
	v_add_f32_e32 v2, v2, v150
	v_mov_b32_e32 v150, v2
	s_nop 1
	v_permlane32_swap_b32_e32 v2, v150
	v_add_f32_e32 v2, v2, v150
	v_fmamk_f32 v2, v2, 0x3c800000, v211
	v_rsq_f32_e32 v2, v2
	s_nop 0
	v_mul_f32_e32 v2, s78, v2
	v_pk_mul_f32 v[104:105], v[104:105], v[2:3] op_sel_hi:[1,0]
	v_pk_mul_f32 v[106:107], v[106:107], v[2:3] op_sel_hi:[1,0]
	v_pk_mul_f32 v[100:101], v[100:101], v[2:3] op_sel_hi:[1,0]
	v_pk_mul_f32 v[102:103], v[102:103], v[2:3] op_sel_hi:[1,0]
	v_pk_mul_f32 v[72:73], v[72:73], v[2:3] op_sel_hi:[1,0]
	v_pk_mul_f32 v[74:75], v[74:75], v[2:3] op_sel_hi:[1,0]
	v_pk_mul_f32 v[68:69], v[68:69], v[2:3] op_sel_hi:[1,0]
	v_pk_mul_f32 v[70:71], v[70:71], v[2:3] op_sel_hi:[1,0]
	v_pk_mul_f32 v[104:105], v[104:105], v[176:177]
	v_pk_mul_f32 v[106:107], v[106:107], v[178:179]
	v_pk_mul_f32 v[100:101], v[100:101], v[206:207]
	v_pk_mul_f32 v[102:103], v[102:103], v[208:209]
	v_pk_mul_f32 v[72:73], v[72:73], v[224:225]
	v_pk_mul_f32 v[74:75], v[74:75], v[226:227]
	v_pk_mul_f32 v[68:69], v[68:69], v[228:229]
	v_pk_mul_f32 v[70:71], v[70:71], v[230:231]
	v_cvt_pk_f16_f32 v160, v104, v105
	v_cvt_pk_f16_f32 v161, v106, v107
	v_cvt_pk_f16_f32 v162, v100, v101
	v_cvt_pk_f16_f32 v163, v102, v103
	global_store_dwordx4 v133, v[160:163], s[6:7] sc0 sc1 nt
	v_cvt_pk_f16_f32 v164, v72, v73
	v_cvt_pk_f16_f32 v165, v74, v75
	v_cvt_pk_f16_f32 v166, v68, v69
	v_cvt_pk_f16_f32 v167, v70, v71
	global_store_dwordx4 v133, v[164:167], s[6:7] offset:2048 sc0 sc1 nt
	s_add_u32 s6, s4, 0x20000
	s_addc_u32 s7, s5, 0
	v_pk_mul_f32 v[64:65], v[64:65], v[142:143] op_sel_hi:[1,0]
	v_pk_mul_f32 v[66:67], v[66:67], v[142:143] op_sel_hi:[1,0]
	v_pk_mul_f32 v[60:61], v[60:61], v[142:143] op_sel_hi:[1,0]
	v_pk_mul_f32 v[62:63], v[62:63], v[142:143] op_sel_hi:[1,0]
	v_pk_mul_f32 v[32:33], v[32:33], v[142:143] op_sel_hi:[1,0]
	v_pk_mul_f32 v[34:35], v[34:35], v[142:143] op_sel_hi:[1,0]
	v_pk_mul_f32 v[28:29], v[28:29], v[142:143] op_sel_hi:[1,0]
	v_pk_mul_f32 v[30:31], v[30:31], v[142:143] op_sel_hi:[1,0]
	v_mul_f32_e32 v2, v64, v64
	v_mul_f32_e32 v150, v65, v65
	v_fmac_f32_e32 v2, v66, v66
	v_fmac_f32_e32 v150, v67, v67
	v_fmac_f32_e32 v2, v60, v60
	v_fmac_f32_e32 v150, v61, v61
	v_fmac_f32_e32 v2, v62, v62
	v_fmac_f32_e32 v150, v63, v63
	v_fmac_f32_e32 v2, v32, v32
	v_fmac_f32_e32 v150, v33, v33
	v_fmac_f32_e32 v2, v34, v34
	v_fmac_f32_e32 v150, v35, v35
	v_fmac_f32_e32 v2, v28, v28
	v_fmac_f32_e32 v150, v29, v29
	v_fmac_f32_e32 v2, v30, v30
	v_fmac_f32_e32 v150, v31, v31
	v_add_f32_e32 v2, v2, v150
	v_mov_b32_e32 v150, v2
	s_nop 1
	v_permlane16_swap_b32_e32 v2, v150
	v_add_f32_e32 v2, v2, v150
	v_mov_b32_e32 v150, v2
	s_nop 1
	v_permlane32_swap_b32_e32 v2, v150
	v_add_f32_e32 v2, v2, v150
	v_fmamk_f32 v2, v2, 0x3c800000, v211
	v_rsq_f32_e32 v2, v2
	s_nop 0
	v_mul_f32_e32 v2, s78, v2
	v_pk_mul_f32 v[64:65], v[64:65], v[2:3] op_sel_hi:[1,0]
	v_pk_mul_f32 v[66:67], v[66:67], v[2:3] op_sel_hi:[1,0]
	v_pk_mul_f32 v[60:61], v[60:61], v[2:3] op_sel_hi:[1,0]
	v_pk_mul_f32 v[62:63], v[62:63], v[2:3] op_sel_hi:[1,0]
	v_pk_mul_f32 v[32:33], v[32:33], v[2:3] op_sel_hi:[1,0]
	v_pk_mul_f32 v[34:35], v[34:35], v[2:3] op_sel_hi:[1,0]
	v_pk_mul_f32 v[28:29], v[28:29], v[2:3] op_sel_hi:[1,0]
	v_pk_mul_f32 v[30:31], v[30:31], v[2:3] op_sel_hi:[1,0]
	v_pk_mul_f32 v[64:65], v[64:65], v[176:177]
	v_pk_mul_f32 v[66:67], v[66:67], v[178:179]
	v_pk_mul_f32 v[60:61], v[60:61], v[206:207]
	v_pk_mul_f32 v[62:63], v[62:63], v[208:209]
	v_pk_mul_f32 v[32:33], v[32:33], v[224:225]
	v_pk_mul_f32 v[34:35], v[34:35], v[226:227]
	v_pk_mul_f32 v[28:29], v[28:29], v[228:229]
	v_pk_mul_f32 v[30:31], v[30:31], v[230:231]
	v_cvt_pk_f16_f32 v152, v64, v65
	v_cvt_pk_f16_f32 v153, v66, v67
	v_cvt_pk_f16_f32 v154, v60, v61
	v_cvt_pk_f16_f32 v155, v62, v63
	global_store_dwordx4 v133, v[152:155], s[6:7] sc0 sc1 nt
	v_cvt_pk_f16_f32 v156, v32, v33
	v_cvt_pk_f16_f32 v157, v34, v35
	v_cvt_pk_f16_f32 v158, v28, v29
	v_cvt_pk_f16_f32 v159, v30, v31
	global_store_dwordx4 v133, v[156:159], s[6:7] offset:2048 sc0 sc1 nt
	s_add_u32 s6, s4, 0x20100
	s_addc_u32 s7, s5, 0
	v_pk_mul_f32 v[56:57], v[56:57], v[144:145] op_sel_hi:[1,0]
	v_pk_mul_f32 v[58:59], v[58:59], v[144:145] op_sel_hi:[1,0]
	v_pk_mul_f32 v[52:53], v[52:53], v[144:145] op_sel_hi:[1,0]
	v_pk_mul_f32 v[54:55], v[54:55], v[144:145] op_sel_hi:[1,0]
	v_pk_mul_f32 v[24:25], v[24:25], v[144:145] op_sel_hi:[1,0]
	v_pk_mul_f32 v[26:27], v[26:27], v[144:145] op_sel_hi:[1,0]
	v_pk_mul_f32 v[20:21], v[20:21], v[144:145] op_sel_hi:[1,0]
	v_pk_mul_f32 v[22:23], v[22:23], v[144:145] op_sel_hi:[1,0]
	v_mul_f32_e32 v2, v56, v56
	v_mul_f32_e32 v150, v57, v57
	v_fmac_f32_e32 v2, v58, v58
	v_fmac_f32_e32 v150, v59, v59
	v_fmac_f32_e32 v2, v52, v52
	v_fmac_f32_e32 v150, v53, v53
	v_fmac_f32_e32 v2, v54, v54
	v_fmac_f32_e32 v150, v55, v55
	v_fmac_f32_e32 v2, v24, v24
	v_fmac_f32_e32 v150, v25, v25
	v_fmac_f32_e32 v2, v26, v26
	v_fmac_f32_e32 v150, v27, v27
	v_fmac_f32_e32 v2, v20, v20
; __device__ __forceinline__ float row4_sum(float s) {
;     { const auto r = __builtin_amdgcn_permlane16_swap(__float_as_uint(s), __float_as_uint(s), false, false); s = __uint_as_float(r[0]) + __uint_as_float(r[1]); }
;     { const auto r = __builtin_amdgcn_permlane32_swap(__float_as_uint(s), __float_as_uint(s), false, false); s = __uint_as_float(r[0]) + __uint_as_float(r[1]); }
;     __device__ __forceinline__ void operator()(const f32x4 (&acc)[2][2][4][2], const Unit& u, int wr, int wc, int fr, int fq) const {
;     ...
;                 f32x4 v[2][2];
; #pragma unroll
;                 for (int bj = 0; bj < 2; ++bj)
; #pragma unroll
;                     for (int n = 0; n < 2; ++n) v[bj][n] = acc[ai][bj][m][n] * rs;
;                 if (sec == 4 || sec == 5) {
;                     float ss = 0.f;
; #pragma unroll
;                     for (int bj = 0; bj < 2; ++bj)
; #pragma unroll
;                         for (int n = 0; n < 2; ++n) { const f32x4 x = v[bj][n]; ss += (x[0] * x[0] + x[1] * x[1]) + (x[2] * x[2] + x[3] * x[3]); }
;                     ss = row4_sum(ss);
;                     float rn = __builtin_amdgcn_rsqf(ss * (1.0f / 64.0f) + RMS_EPS);
;                     if (sec == 4) rn *= QS;
; #pragma unroll
;                     for (int bj = 0; bj < 2; ++bj)
; #pragma unroll
;                         for (int n = 0; n < 2; ++n) v[bj][n] = v[bj][n] * rn * gain[bj][n];
;                 } else if (sec == 0) {
; #pragma unroll
;                     for (int bj = 0; bj < 2; ++bj)
; #pragma unroll
;                         for (int n = 0; n < 2; ++n) v[bj][n] = v[bj][n] * QS;
;                 } else if (sec == 3 || sec == 7) {
; #pragma unroll
;                     for (int bj = 0; bj < 2; ++bj)
; #pragma unroll
;                         for (int n = 0; n < 2; ++n)
; #pragma unroll
;                             for (int e = 0; e < 4; ++e) v[bj][n][e] = silu_f(v[bj][n][e]);
;                 }
;                 GAS f16* rowp = isqg ? QG + (size_t)dsec * QG_SEC + bl512((size_t)row, cs) : KV + (size_t)row * KVW + dsec * 512 + cs;
; #pragma unroll
;                 for (int bj = 0; bj < 2; ++bj) {
;                     u32x4 w; w.x = pkh(v[bj][0][0], v[bj][0][1]); w.y = pkh(v[bj][0][2], v[bj][0][3]); w.z = pkh(v[bj][1][0], v[bj][1][1]); w.w = pkh(v[bj][1][2], v[bj][1][3]);
;                     *(GAS u32x4*)(rowp + bjstep * bj) = w;
;                 }
	v_fmac_f32_e32 v150, v21, v21
	v_fmac_f32_e32 v2, v22, v22
	v_fmac_f32_e32 v150, v23, v23
	v_add_f32_e32 v2, v2, v150
	v_mov_b32_e32 v150, v2
	s_nop 1
	v_permlane16_swap_b32_e32 v2, v150
	v_add_f32_e32 v2, v2, v150
	v_mov_b32_e32 v150, v2
	s_nop 1
	v_permlane32_swap_b32_e32 v2, v150
	v_add_f32_e32 v2, v2, v150
	v_fmamk_f32 v2, v2, 0x3c800000, v211
	v_rsq_f32_e32 v2, v2
	s_nop 0
	v_mul_f32_e32 v2, s78, v2
	v_pk_mul_f32 v[56:57], v[56:57], v[2:3] op_sel_hi:[1,0]
	v_pk_mul_f32 v[58:59], v[58:59], v[2:3] op_sel_hi:[1,0]
	v_pk_mul_f32 v[52:53], v[52:53], v[2:3] op_sel_hi:[1,0]
	v_pk_mul_f32 v[54:55], v[54:55], v[2:3] op_sel_hi:[1,0]
	v_pk_mul_f32 v[24:25], v[24:25], v[2:3] op_sel_hi:[1,0]
	v_pk_mul_f32 v[26:27], v[26:27], v[2:3] op_sel_hi:[1,0]
	v_pk_mul_f32 v[20:21], v[20:21], v[2:3] op_sel_hi:[1,0]
	v_pk_mul_f32 v[22:23], v[22:23], v[2:3] op_sel_hi:[1,0]
	v_pk_mul_f32 v[56:57], v[56:57], v[176:177]
	v_pk_mul_f32 v[58:59], v[58:59], v[178:179]
	v_pk_mul_f32 v[52:53], v[52:53], v[206:207]
	v_pk_mul_f32 v[54:55], v[54:55], v[208:209]
	v_pk_mul_f32 v[24:25], v[24:25], v[224:225]
	v_pk_mul_f32 v[26:27], v[26:27], v[226:227]
	v_pk_mul_f32 v[20:21], v[20:21], v[228:229]
	v_pk_mul_f32 v[22:23], v[22:23], v[230:231]
	v_cvt_pk_f16_f32 v160, v56, v57
	v_cvt_pk_f16_f32 v161, v58, v59
	v_cvt_pk_f16_f32 v162, v52, v53
	v_cvt_pk_f16_f32 v163, v54, v55
	global_store_dwordx4 v133, v[160:163], s[6:7] sc0 sc1 nt
	v_cvt_pk_f16_f32 v164, v24, v25
	v_cvt_pk_f16_f32 v165, v26, v27
	v_cvt_pk_f16_f32 v166, v20, v21
	v_cvt_pk_f16_f32 v167, v22, v23
	global_store_dwordx4 v133, v[164:167], s[6:7] offset:2048 sc0 sc1 nt
	s_add_u32 s6, s4, 0x28000
	s_addc_u32 s7, s5, 0
	v_pk_mul_f32 v[48:49], v[48:49], v[146:147] op_sel_hi:[1,0]
	v_pk_mul_f32 v[50:51], v[50:51], v[146:147] op_sel_hi:[1,0]
	v_pk_mul_f32 v[44:45], v[44:45], v[146:147] op_sel_hi:[1,0]
	v_pk_mul_f32 v[46:47], v[46:47], v[146:147] op_sel_hi:[1,0]
	v_pk_mul_f32 v[16:17], v[16:17], v[146:147] op_sel_hi:[1,0]
	v_pk_mul_f32 v[18:19], v[18:19], v[146:147] op_sel_hi:[1,0]
	v_pk_mul_f32 v[12:13], v[12:13], v[146:147] op_sel_hi:[1,0]
	v_pk_mul_f32 v[14:15], v[14:15], v[146:147] op_sel_hi:[1,0]
	v_mul_f32_e32 v2, v48, v48
	v_mul_f32_e32 v150, v49, v49
	v_fmac_f32_e32 v2, v50, v50
	v_fmac_f32_e32 v150, v51, v51
	v_fmac_f32_e32 v2, v44, v44
	v_fmac_f32_e32 v150, v45, v45
	v_fmac_f32_e32 v2, v46, v46
	v_fmac_f32_e32 v150, v47, v47
	v_fmac_f32_e32 v2, v16, v16
	v_fmac_f32_e32 v150, v17, v17
	v_fmac_f32_e32 v2, v18, v18
	v_fmac_f32_e32 v150, v19, v19
	v_fmac_f32_e32 v2, v12, v12
	v_fmac_f32_e32 v150, v13, v13
	v_fmac_f32_e32 v2, v14, v14
	v_fmac_f32_e32 v150, v15, v15
	v_add_f32_e32 v2, v2, v150
	v_mov_b32_e32 v150, v2
	s_nop 1
	v_permlane16_swap_b32_e32 v2, v150
	v_add_f32_e32 v2, v2, v150
	v_mov_b32_e32 v150, v2
	s_nop 1
	v_permlane32_swap_b32_e32 v2, v150
	v_add_f32_e32 v2, v2, v150
	v_fmamk_f32 v2, v2, 0x3c800000, v211
	v_rsq_f32_e32 v2, v2
	s_nop 0
	v_mul_f32_e32 v2, s78, v2
	v_pk_mul_f32 v[48:49], v[48:49], v[2:3] op_sel_hi:[1,0]
	v_pk_mul_f32 v[50:51], v[50:51], v[2:3] op_sel_hi:[1,0]
	v_pk_mul_f32 v[44:45], v[44:45], v[2:3] op_sel_hi:[1,0]
	v_pk_mul_f32 v[46:47], v[46:47], v[2:3] op_sel_hi:[1,0]
	v_pk_mul_f32 v[16:17], v[16:17], v[2:3] op_sel_hi:[1,0]
	v_pk_mul_f32 v[18:19], v[18:19], v[2:3] op_sel_hi:[1,0]
	v_pk_mul_f32 v[12:13], v[12:13], v[2:3] op_sel_hi:[1,0]
	v_pk_mul_f32 v[14:15], v[14:15], v[2:3] op_sel_hi:[1,0]
	v_pk_mul_f32 v[48:49], v[48:49], v[176:177]
	v_pk_mul_f32 v[50:51], v[50:51], v[178:179]
	v_pk_mul_f32 v[44:45], v[44:45], v[206:207]
	v_pk_mul_f32 v[46:47], v[46:47], v[208:209]
	v_pk_mul_f32 v[16:17], v[16:17], v[224:225]
	v_pk_mul_f32 v[18:19], v[18:19], v[226:227]
	v_pk_mul_f32 v[12:13], v[12:13], v[228:229]
	v_pk_mul_f32 v[14:15], v[14:15], v[230:231]
	v_cvt_pk_f16_f32 v152, v48, v49
	v_cvt_pk_f16_f32 v153, v50, v51
	v_cvt_pk_f16_f32 v154, v44, v45
	v_cvt_pk_f16_f32 v155, v46, v47
	global_store_dwordx4 v133, v[152:155], s[6:7] sc0 sc1 nt
	v_cvt_pk_f16_f32 v156, v16, v17
	v_cvt_pk_f16_f32 v157, v18, v19
	v_cvt_pk_f16_f32 v158, v12, v13
	v_cvt_pk_f16_f32 v159, v14, v15
	global_store_dwordx4 v133, v[156:159], s[6:7] offset:2048 sc0 sc1 nt
	s_add_u32 s6, s4, 0x28100
	s_addc_u32 s7, s5, 0
	v_pk_mul_f32 v[40:41], v[40:41], v[148:149] op_sel_hi:[1,0]
	v_pk_mul_f32 v[42:43], v[42:43], v[148:149] op_sel_hi:[1,0]
	v_pk_mul_f32 v[36:37], v[36:37], v[148:149] op_sel_hi:[1,0]
	v_pk_mul_f32 v[38:39], v[38:39], v[148:149] op_sel_hi:[1,0]
	v_pk_mul_f32 v[8:9], v[8:9], v[148:149] op_sel_hi:[1,0]
	v_pk_mul_f32 v[10:11], v[10:11], v[148:149] op_sel_hi:[1,0]
	v_pk_mul_f32 v[4:5], v[4:5], v[148:149] op_sel_hi:[1,0]
	v_pk_mul_f32 v[6:7], v[6:7], v[148:149] op_sel_hi:[1,0]
	v_mul_f32_e32 v2, v40, v40
	v_mul_f32_e32 v150, v41, v41
	v_fmac_f32_e32 v2, v42, v42
	v_fmac_f32_e32 v150, v43, v43
	v_fmac_f32_e32 v2, v36, v36
	v_fmac_f32_e32 v150, v37, v37
	v_fmac_f32_e32 v2, v38, v38
	v_fmac_f32_e32 v150, v39, v39
	v_fmac_f32_e32 v2, v8, v8
	v_fmac_f32_e32 v150, v9, v9
	v_fmac_f32_e32 v2, v10, v10
	v_fmac_f32_e32 v150, v11, v11
	v_fmac_f32_e32 v2, v4, v4
	v_fmac_f32_e32 v150, v5, v5
	v_fmac_f32_e32 v2, v6, v6
	v_fmac_f32_e32 v150, v7, v7
	v_add_f32_e32 v2, v2, v150
	v_mov_b32_e32 v150, v2
	s_nop 1
	v_permlane16_swap_b32_e32 v2, v150
	v_add_f32_e32 v2, v2, v150
	v_mov_b32_e32 v150, v2
	s_nop 1
	v_permlane32_swap_b32_e32 v2, v150
	v_add_f32_e32 v2, v2, v150
	v_fmamk_f32 v2, v2, 0x3c800000, v211
	v_rsq_f32_e32 v2, v2
	s_nop 0
	v_mul_f32_e32 v2, s78, v2
	v_pk_mul_f32 v[40:41], v[40:41], v[2:3] op_sel_hi:[1,0]
	v_pk_mul_f32 v[42:43], v[42:43], v[2:3] op_sel_hi:[1,0]
	v_pk_mul_f32 v[36:37], v[36:37], v[2:3] op_sel_hi:[1,0]
	v_pk_mul_f32 v[38:39], v[38:39], v[2:3] op_sel_hi:[1,0]
	v_pk_mul_f32 v[8:9], v[8:9], v[2:3] op_sel_hi:[1,0]
	v_pk_mul_f32 v[10:11], v[10:11], v[2:3] op_sel_hi:[1,0]
	v_pk_mul_f32 v[4:5], v[4:5], v[2:3] op_sel_hi:[1,0]
	v_pk_mul_f32 v[6:7], v[6:7], v[2:3] op_sel_hi:[1,0]
	v_pk_mul_f32 v[40:41], v[40:41], v[176:177]
	v_pk_mul_f32 v[42:43], v[42:43], v[178:179]
	v_pk_mul_f32 v[36:37], v[36:37], v[206:207]
	v_pk_mul_f32 v[38:39], v[38:39], v[208:209]
	v_pk_mul_f32 v[8:9], v[8:9], v[224:225]
	v_pk_mul_f32 v[10:11], v[10:11], v[226:227]
	v_pk_mul_f32 v[4:5], v[4:5], v[228:229]
	v_pk_mul_f32 v[6:7], v[6:7], v[230:231]
	v_cvt_pk_f16_f32 v160, v40, v41
	v_cvt_pk_f16_f32 v161, v42, v43
	v_cvt_pk_f16_f32 v162, v36, v37
	v_cvt_pk_f16_f32 v163, v38, v39
	global_store_dwordx4 v133, v[160:163], s[6:7] sc0 sc1 nt
	v_cvt_pk_f16_f32 v164, v8, v9
	v_cvt_pk_f16_f32 v165, v10, v11
	v_cvt_pk_f16_f32 v166, v4, v5
	v_cvt_pk_f16_f32 v167, v6, v7
	global_store_dwordx4 v133, v[164:167], s[6:7] offset:2048 sc0 sc1 nt
	s_branch .Lepi_done_g1
;     __device__ __forceinline__ void operator()(const f32x4 (&acc)[2][2][4][2], const Unit& u, int wr, int wc, int fr, int fq) const {
;     ...
;         if (sec == 4 || sec == 5) {
;             const GAS float* g = (sec == 4) ? gq : gk;
; #pragma unroll
;             for (int bj = 0; bj < 2; ++bj)
; #pragma unroll
;                 for (int n = 0; n < 2; ++n) gain[bj][n] = *(const GAS f32x4*)(g + 32 * bj + 8 * fq + 4 * n);
;         }
;         const LAS int* tags = (const LAS int*)(rsc + 2048);
;         const int slot = (tags[0] == u.pm) ? 0 : (tags[1] == u.pm) ? 1 : -1;
;         const LAS float* rtab = (const LAS float*)rsc + (slot > 0 ? 256 : 0) + wr * 64 + fr;
; #pragma unroll
;         for (int ai = 0; ai < 2; ++ai)
; #pragma unroll
;             for (int m = 0; m < 4; ++m) {
;                 const int row = row0 + ai * HALF + m * 16;
;                 float rs;
;                 if (slot >= 0) rs = rtab[ai * HALF + m * 16];
;                 else {
;                     const f32x4 pv = *(const GAS f32x4*)(part + (size_t)row * 16 + fq * 4);
;                     float s = (pv[0] + pv[1]) + (pv[2] + pv[3]);
;                     s = row4_sum(s);
;                     rs = __builtin_amdgcn_rsqf(s * (1.0f / DM) + RMS_EPS);
;                 }
;                 f32x4 v[2][2];
; #pragma unroll
;                 for (int bj = 0; bj < 2; ++bj)
; #pragma unroll
;                     for (int n = 0; n < 2; ++n) v[bj][n] = acc[ai][bj][m][n] * rs;
;                 if (sec == 4 || sec == 5) {
;                     float ss = 0.f;
; #pragma unroll
;                     for (int bj = 0; bj < 2; ++bj)
; #pragma unroll
;                         for (int n = 0; n < 2; ++n) { const f32x4 x = v[bj][n]; ss += (x[0] * x[0] + x[1] * x[1]) + (x[2] * x[2] + x[3] * x[3]); }
;                     ss = row4_sum(ss);
;                     float rn = __builtin_amdgcn_rsqf(ss * (1.0f / 64.0f) + RMS_EPS);
;                     if (sec == 4) rn *= QS;
; #pragma unroll
;                     for (int bj = 0; bj < 2; ++bj)
; #pragma unroll
;                         for (int n = 0; n < 2; ++n) v[bj][n] = v[bj][n] * rn * gain[bj][n];
;                 } else if (sec == 0) {
; #pragma unroll
;                     for (int bj = 0; bj < 2; ++bj)
; #pragma unroll
;                         for (int n = 0; n < 2; ++n) v[bj][n] = v[bj][n] * QS;
;                 } else if (sec == 3 || sec == 7) {
.Lepi_kn:
	s_and_b32 s0, s70, 1
	s_lshl_b32 s0, s0, 10
	v_add_u32_e32 v132, s0, v219
	ds_read_b32 v134, v132
	ds_read_b32 v136, v132 offset:64
	ds_read_b32 v138, v132 offset:128
	ds_read_b32 v140, v132 offset:192
	ds_read_b32 v142, v132 offset:512
	ds_read_b32 v144, v132 offset:576
	ds_read_b32 v146, v132 offset:640
	ds_read_b32 v148, v132 offset:704
	s_lshr_b32 s0, s69, 2
	s_and_b32 s1, s69, 1
	v_lshl_add_u32 v133, s68, 8, v187
	v_lshlrev_b32_e32 v133, 12, v133
	v_lshl_add_u32 v133, v220, 1, v133
	s_lshl_b32 s0, s0, 10
	s_lshl_b32 s1, s1, 9
	s_add_u32 s0, s0, s1
	s_add_u32 s4, s8, s0
	s_addc_u32 s5, s9, 0
	v_readlane_b32 s10, v252, 19
	v_readlane_b32 s11, v252, 20
	s_lshl_b32 s0, s22, 2
	s_nop 0
	s_add_u32 s10, s10, s0
	s_addc_u32 s11, s11, 0
	s_nop 3
	global_load_dwordx4 v[176:179], v222, s[10:11]
	global_load_dwordx4 v[206:209], v222, s[10:11] offset:16
	global_load_dwordx4 v[224:227], v222, s[10:11] offset:128
	global_load_dwordx4 v[228:231], v222, s[10:11] offset:144
	s_waitcnt vmcnt(0)
	s_waitcnt lgkmcnt(0)
	s_mov_b32 s6, s4
	s_mov_b32 s7, s5
	v_pk_mul_f32 v[128:129], v[128:129], v[134:135] op_sel_hi:[1,0]
	v_pk_mul_f32 v[130:131], v[130:131], v[134:135] op_sel_hi:[1,0]
	v_pk_mul_f32 v[124:125], v[124:125], v[134:135] op_sel_hi:[1,0]
	v_pk_mul_f32 v[126:127], v[126:127], v[134:135] op_sel_hi:[1,0]
	v_pk_mul_f32 v[96:97], v[96:97], v[134:135] op_sel_hi:[1,0]
	v_pk_mul_f32 v[98:99], v[98:99], v[134:135] op_sel_hi:[1,0]
	v_pk_mul_f32 v[92:93], v[92:93], v[134:135] op_sel_hi:[1,0]
	v_pk_mul_f32 v[94:95], v[94:95], v[134:135] op_sel_hi:[1,0]
	v_mul_f32_e32 v2, v128, v128
	v_mul_f32_e32 v150, v129, v129
	v_fmac_f32_e32 v2, v130, v130
	v_fmac_f32_e32 v150, v131, v131
	v_fmac_f32_e32 v2, v124, v124
	v_fmac_f32_e32 v150, v125, v125
	v_fmac_f32_e32 v2, v126, v126
	v_fmac_f32_e32 v150, v127, v127
	v_fmac_f32_e32 v2, v96, v96
	v_fmac_f32_e32 v150, v97, v97
	v_fmac_f32_e32 v2, v98, v98
	v_fmac_f32_e32 v150, v99, v99
	v_fmac_f32_e32 v2, v92, v92
	v_fmac_f32_e32 v150, v93, v93
	v_fmac_f32_e32 v2, v94, v94
	v_fmac_f32_e32 v150, v95, v95
	v_add_f32_e32 v2, v2, v150
	v_mov_b32_e32 v150, v2
	s_nop 1
	v_permlane16_swap_b32_e32 v2, v150
	v_add_f32_e32 v2, v2, v150
	v_mov_b32_e32 v150, v2
	s_nop 1
	v_permlane32_swap_b32_e32 v2, v150
	v_add_f32_e32 v2, v2, v150
	v_fmamk_f32 v2, v2, 0x3c800000, v211
	v_rsq_f32_e32 v2, v2
	s_nop 0
	v_pk_mul_f32 v[128:129], v[128:129], v[2:3] op_sel_hi:[1,0]
	v_pk_mul_f32 v[130:131], v[130:131], v[2:3] op_sel_hi:[1,0]
	v_pk_mul_f32 v[124:125], v[124:125], v[2:3] op_sel_hi:[1,0]
	v_pk_mul_f32 v[126:127], v[126:127], v[2:3] op_sel_hi:[1,0]
	v_pk_mul_f32 v[96:97], v[96:97], v[2:3] op_sel_hi:[1,0]
	v_pk_mul_f32 v[98:99], v[98:99], v[2:3] op_sel_hi:[1,0]
	v_pk_mul_f32 v[92:93], v[92:93], v[2:3] op_sel_hi:[1,0]
	v_pk_mul_f32 v[94:95], v[94:95], v[2:3] op_sel_hi:[1,0]
	v_pk_mul_f32 v[128:129], v[128:129], v[176:177]
	v_pk_mul_f32 v[130:131], v[130:131], v[178:179]
	v_pk_mul_f32 v[124:125], v[124:125], v[206:207]
	v_pk_mul_f32 v[126:127], v[126:127], v[208:209]
	v_pk_mul_f32 v[96:97], v[96:97], v[224:225]
	v_pk_mul_f32 v[98:99], v[98:99], v[226:227]
	v_pk_mul_f32 v[92:93], v[92:93], v[228:229]
	v_pk_mul_f32 v[94:95], v[94:95], v[230:231]
	v_cvt_pk_f16_f32 v152, v128, v129
	v_cvt_pk_f16_f32 v153, v130, v131
	v_cvt_pk_f16_f32 v154, v124, v125
	v_cvt_pk_f16_f32 v155, v126, v127
	global_store_dwordx4 v133, v[152:155], s[6:7] sc0 sc1 nt
	v_cvt_pk_f16_f32 v156, v96, v97
	v_cvt_pk_f16_f32 v157, v98, v99
	v_cvt_pk_f16_f32 v158, v92, v93
	v_cvt_pk_f16_f32 v159, v94, v95
	global_store_dwordx4 v133, v[156:159], s[6:7] offset:64 sc0 sc1 nt
	s_add_u32 s6, s4, 0x10000
	s_addc_u32 s7, s5, 0
	v_pk_mul_f32 v[120:121], v[120:121], v[136:137] op_sel_hi:[1,0]
	v_pk_mul_f32 v[122:123], v[122:123], v[136:137] op_sel_hi:[1,0]
	v_pk_mul_f32 v[116:117], v[116:117], v[136:137] op_sel_hi:[1,0]
	v_pk_mul_f32 v[118:119], v[118:119], v[136:137] op_sel_hi:[1,0]
	v_pk_mul_f32 v[88:89], v[88:89], v[136:137] op_sel_hi:[1,0]
	v_pk_mul_f32 v[90:91], v[90:91], v[136:137] op_sel_hi:[1,0]
	v_pk_mul_f32 v[84:85], v[84:85], v[136:137] op_sel_hi:[1,0]
	v_pk_mul_f32 v[86:87], v[86:87], v[136:137] op_sel_hi:[1,0]
	v_mul_f32_e32 v2, v120, v120
	v_mul_f32_e32 v150, v121, v121
	v_fmac_f32_e32 v2, v122, v122
	v_fmac_f32_e32 v150, v123, v123
	v_fmac_f32_e32 v2, v116, v116
	v_fmac_f32_e32 v150, v117, v117
	v_fmac_f32_e32 v2, v118, v118
	v_fmac_f32_e32 v150, v119, v119
	v_fmac_f32_e32 v2, v88, v88
	v_fmac_f32_e32 v150, v89, v89
	v_fmac_f32_e32 v2, v90, v90
	v_fmac_f32_e32 v150, v91, v91
	v_fmac_f32_e32 v2, v84, v84
	v_fmac_f32_e32 v150, v85, v85
	v_fmac_f32_e32 v2, v86, v86
	v_fmac_f32_e32 v150, v87, v87
	v_add_f32_e32 v2, v2, v150
	v_mov_b32_e32 v150, v2
	s_nop 1
	v_permlane16_swap_b32_e32 v2, v150
	v_add_f32_e32 v2, v2, v150
	v_mov_b32_e32 v150, v2
	s_nop 1
	v_permlane32_swap_b32_e32 v2, v150
	v_add_f32_e32 v2, v2, v150
	v_fmamk_f32 v2, v2, 0x3c800000, v211
	v_rsq_f32_e32 v2, v2
	s_nop 0
	v_pk_mul_f32 v[120:121], v[120:121], v[2:3] op_sel_hi:[1,0]
	v_pk_mul_f32 v[122:123], v[122:123], v[2:3] op_sel_hi:[1,0]
	v_pk_mul_f32 v[116:117], v[116:117], v[2:3] op_sel_hi:[1,0]
	v_pk_mul_f32 v[118:119], v[118:119], v[2:3] op_sel_hi:[1,0]
	v_pk_mul_f32 v[88:89], v[88:89], v[2:3] op_sel_hi:[1,0]
	v_pk_mul_f32 v[90:91], v[90:91], v[2:3] op_sel_hi:[1,0]
	v_pk_mul_f32 v[84:85], v[84:85], v[2:3] op_sel_hi:[1,0]
	v_pk_mul_f32 v[86:87], v[86:87], v[2:3] op_sel_hi:[1,0]
	v_pk_mul_f32 v[120:121], v[120:121], v[176:177]
	v_pk_mul_f32 v[122:123], v[122:123], v[178:179]
	v_pk_mul_f32 v[116:117], v[116:117], v[206:207]
	v_pk_mul_f32 v[118:119], v[118:119], v[208:209]
	v_pk_mul_f32 v[88:89], v[88:89], v[224:225]
; __device__ __forceinline__ float row4_sum(float s) {
;     { const auto r = __builtin_amdgcn_permlane16_swap(__float_as_uint(s), __float_as_uint(s), false, false); s = __uint_as_float(r[0]) + __uint_as_float(r[1]); }
;     { const auto r = __builtin_amdgcn_permlane32_swap(__float_as_uint(s), __float_as_uint(s), false, false); s = __uint_as_float(r[0]) + __uint_as_float(r[1]); }
;     __device__ __forceinline__ void operator()(const f32x4 (&acc)[2][2][4][2], const Unit& u, int wr, int wc, int fr, int fq) const {
;     ...
;                 f32x4 v[2][2];
; #pragma unroll
;                 for (int bj = 0; bj < 2; ++bj)
; #pragma unroll
;                     for (int n = 0; n < 2; ++n) v[bj][n] = acc[ai][bj][m][n] * rs;
;                 if (sec == 4 || sec == 5) {
;                     float ss = 0.f;
; #pragma unroll
;                     for (int bj = 0; bj < 2; ++bj)
; #pragma unroll
;                         for (int n = 0; n < 2; ++n) { const f32x4 x = v[bj][n]; ss += (x[0] * x[0] + x[1] * x[1]) + (x[2] * x[2] + x[3] * x[3]); }
;                     ss = row4_sum(ss);
;                     float rn = __builtin_amdgcn_rsqf(ss * (1.0f / 64.0f) + RMS_EPS);
;                     if (sec == 4) rn *= QS;
; #pragma unroll
;                     for (int bj = 0; bj < 2; ++bj)
; #pragma unroll
;                         for (int n = 0; n < 2; ++n) v[bj][n] = v[bj][n] * rn * gain[bj][n];
;                 } else if (sec == 0) {
; #pragma unroll
;                     for (int bj = 0; bj < 2; ++bj)
; #pragma unroll
;                         for (int n = 0; n < 2; ++n) v[bj][n] = v[bj][n] * QS;
;                 } else if (sec == 3 || sec == 7) {
; #pragma unroll
;                     for (int bj = 0; bj < 2; ++bj)
; #pragma unroll
;                         for (int n = 0; n < 2; ++n)
; #pragma unroll
;                             for (int e = 0; e < 4; ++e) v[bj][n][e] = silu_f(v[bj][n][e]);
;                 }
;                 GAS f16* rowp = isqg ? QG + (size_t)dsec * QG_SEC + bl512((size_t)row, cs) : KV + (size_t)row * KVW + dsec * 512 + cs;
; #pragma unroll
;                 for (int bj = 0; bj < 2; ++bj) {
;                     u32x4 w; w.x = pkh(v[bj][0][0], v[bj][0][1]); w.y = pkh(v[bj][0][2], v[bj][0][3]); w.z = pkh(v[bj][1][0], v[bj][1][1]); w.w = pkh(v[bj][1][2], v[bj][1][3]);
;                     *(GAS u32x4*)(rowp + bjstep * bj) = w;
;                 }
	v_pk_mul_f32 v[90:91], v[90:91], v[226:227]
	v_pk_mul_f32 v[84:85], v[84:85], v[228:229]
	v_pk_mul_f32 v[86:87], v[86:87], v[230:231]
	v_cvt_pk_f16_f32 v160, v120, v121
	v_cvt_pk_f16_f32 v161, v122, v123
	v_cvt_pk_f16_f32 v162, v116, v117
	v_cvt_pk_f16_f32 v163, v118, v119
	global_store_dwordx4 v133, v[160:163], s[6:7] sc0 sc1 nt
	v_cvt_pk_f16_f32 v164, v88, v89
	v_cvt_pk_f16_f32 v165, v90, v91
	v_cvt_pk_f16_f32 v166, v84, v85
	v_cvt_pk_f16_f32 v167, v86, v87
	global_store_dwordx4 v133, v[164:167], s[6:7] offset:64 sc0 sc1 nt
	s_add_u32 s6, s4, 0x20000
	s_addc_u32 s7, s5, 0
	v_pk_mul_f32 v[112:113], v[112:113], v[138:139] op_sel_hi:[1,0]
	v_pk_mul_f32 v[114:115], v[114:115], v[138:139] op_sel_hi:[1,0]
	v_pk_mul_f32 v[108:109], v[108:109], v[138:139] op_sel_hi:[1,0]
	v_pk_mul_f32 v[110:111], v[110:111], v[138:139] op_sel_hi:[1,0]
	v_pk_mul_f32 v[80:81], v[80:81], v[138:139] op_sel_hi:[1,0]
	v_pk_mul_f32 v[82:83], v[82:83], v[138:139] op_sel_hi:[1,0]
	v_pk_mul_f32 v[76:77], v[76:77], v[138:139] op_sel_hi:[1,0]
	v_pk_mul_f32 v[78:79], v[78:79], v[138:139] op_sel_hi:[1,0]
	v_mul_f32_e32 v2, v112, v112
	v_mul_f32_e32 v150, v113, v113
	v_fmac_f32_e32 v2, v114, v114
	v_fmac_f32_e32 v150, v115, v115
	v_fmac_f32_e32 v2, v108, v108
	v_fmac_f32_e32 v150, v109, v109
	v_fmac_f32_e32 v2, v110, v110
	v_fmac_f32_e32 v150, v111, v111
	v_fmac_f32_e32 v2, v80, v80
	v_fmac_f32_e32 v150, v81, v81
	v_fmac_f32_e32 v2, v82, v82
	v_fmac_f32_e32 v150, v83, v83
	v_fmac_f32_e32 v2, v76, v76
	v_fmac_f32_e32 v150, v77, v77
	v_fmac_f32_e32 v2, v78, v78
	v_fmac_f32_e32 v150, v79, v79
	v_add_f32_e32 v2, v2, v150
	v_mov_b32_e32 v150, v2
	s_nop 1
	v_permlane16_swap_b32_e32 v2, v150
	v_add_f32_e32 v2, v2, v150
	v_mov_b32_e32 v150, v2
	s_nop 1
	v_permlane32_swap_b32_e32 v2, v150
	v_add_f32_e32 v2, v2, v150
	v_fmamk_f32 v2, v2, 0x3c800000, v211
	v_rsq_f32_e32 v2, v2
	s_nop 0
	v_pk_mul_f32 v[112:113], v[112:113], v[2:3] op_sel_hi:[1,0]
	v_pk_mul_f32 v[114:115], v[114:115], v[2:3] op_sel_hi:[1,0]
	v_pk_mul_f32 v[108:109], v[108:109], v[2:3] op_sel_hi:[1,0]
	v_pk_mul_f32 v[110:111], v[110:111], v[2:3] op_sel_hi:[1,0]
	v_pk_mul_f32 v[80:81], v[80:81], v[2:3] op_sel_hi:[1,0]
	v_pk_mul_f32 v[82:83], v[82:83], v[2:3] op_sel_hi:[1,0]
	v_pk_mul_f32 v[76:77], v[76:77], v[2:3] op_sel_hi:[1,0]
	v_pk_mul_f32 v[78:79], v[78:79], v[2:3] op_sel_hi:[1,0]
	v_pk_mul_f32 v[112:113], v[112:113], v[176:177]
	v_pk_mul_f32 v[114:115], v[114:115], v[178:179]
	v_pk_mul_f32 v[108:109], v[108:109], v[206:207]
	v_pk_mul_f32 v[110:111], v[110:111], v[208:209]
	v_pk_mul_f32 v[80:81], v[80:81], v[224:225]
	v_pk_mul_f32 v[82:83], v[82:83], v[226:227]
	v_pk_mul_f32 v[76:77], v[76:77], v[228:229]
	v_pk_mul_f32 v[78:79], v[78:79], v[230:231]
	v_cvt_pk_f16_f32 v152, v112, v113
	v_cvt_pk_f16_f32 v153, v114, v115
	v_cvt_pk_f16_f32 v154, v108, v109
	v_cvt_pk_f16_f32 v155, v110, v111
	global_store_dwordx4 v133, v[152:155], s[6:7] sc0 sc1 nt
	v_cvt_pk_f16_f32 v156, v80, v81
	v_cvt_pk_f16_f32 v157, v82, v83
	v_cvt_pk_f16_f32 v158, v76, v77
	v_cvt_pk_f16_f32 v159, v78, v79
	global_store_dwordx4 v133, v[156:159], s[6:7] offset:64 sc0 sc1 nt
	s_add_u32 s6, s4, 0x30000
	s_addc_u32 s7, s5, 0
	v_pk_mul_f32 v[104:105], v[104:105], v[140:141] op_sel_hi:[1,0]
	v_pk_mul_f32 v[106:107], v[106:107], v[140:141] op_sel_hi:[1,0]
	v_pk_mul_f32 v[100:101], v[100:101], v[140:141] op_sel_hi:[1,0]
	v_pk_mul_f32 v[102:103], v[102:103], v[140:141] op_sel_hi:[1,0]
	v_pk_mul_f32 v[72:73], v[72:73], v[140:141] op_sel_hi:[1,0]
	v_pk_mul_f32 v[74:75], v[74:75], v[140:141] op_sel_hi:[1,0]
	v_pk_mul_f32 v[68:69], v[68:69], v[140:141] op_sel_hi:[1,0]
	v_pk_mul_f32 v[70:71], v[70:71], v[140:141] op_sel_hi:[1,0]
	v_mul_f32_e32 v2, v104, v104
	v_mul_f32_e32 v150, v105, v105
	v_fmac_f32_e32 v2, v106, v106
	v_fmac_f32_e32 v150, v107, v107
	v_fmac_f32_e32 v2, v100, v100
	v_fmac_f32_e32 v150, v101, v101
	v_fmac_f32_e32 v2, v102, v102
	v_fmac_f32_e32 v150, v103, v103
	v_fmac_f32_e32 v2, v72, v72
	v_fmac_f32_e32 v150, v73, v73
	v_fmac_f32_e32 v2, v74, v74
	v_fmac_f32_e32 v150, v75, v75
	v_fmac_f32_e32 v2, v68, v68
	v_fmac_f32_e32 v150, v69, v69
	v_fmac_f32_e32 v2, v70, v70
	v_fmac_f32_e32 v150, v71, v71
	v_add_f32_e32 v2, v2, v150
	v_mov_b32_e32 v150, v2
	s_nop 1
	v_permlane16_swap_b32_e32 v2, v150
	v_add_f32_e32 v2, v2, v150
	v_mov_b32_e32 v150, v2
	s_nop 1
	v_permlane32_swap_b32_e32 v2, v150
	v_add_f32_e32 v2, v2, v150
	v_fmamk_f32 v2, v2, 0x3c800000, v211
	v_rsq_f32_e32 v2, v2
	s_nop 0
	v_pk_mul_f32 v[104:105], v[104:105], v[2:3] op_sel_hi:[1,0]
	v_pk_mul_f32 v[106:107], v[106:107], v[2:3] op_sel_hi:[1,0]
	v_pk_mul_f32 v[100:101], v[100:101], v[2:3] op_sel_hi:[1,0]
	v_pk_mul_f32 v[102:103], v[102:103], v[2:3] op_sel_hi:[1,0]
	v_pk_mul_f32 v[72:73], v[72:73], v[2:3] op_sel_hi:[1,0]
	v_pk_mul_f32 v[74:75], v[74:75], v[2:3] op_sel_hi:[1,0]
	v_pk_mul_f32 v[68:69], v[68:69], v[2:3] op_sel_hi:[1,0]
	v_pk_mul_f32 v[70:71], v[70:71], v[2:3] op_sel_hi:[1,0]
	v_pk_mul_f32 v[104:105], v[104:105], v[176:177]
	v_pk_mul_f32 v[106:107], v[106:107], v[178:179]
	v_pk_mul_f32 v[100:101], v[100:101], v[206:207]
	v_pk_mul_f32 v[102:103], v[102:103], v[208:209]
	v_pk_mul_f32 v[72:73], v[72:73], v[224:225]
	v_pk_mul_f32 v[74:75], v[74:75], v[226:227]
	v_pk_mul_f32 v[68:69], v[68:69], v[228:229]
	v_pk_mul_f32 v[70:71], v[70:71], v[230:231]
	v_cvt_pk_f16_f32 v160, v104, v105
	v_cvt_pk_f16_f32 v161, v106, v107
	v_cvt_pk_f16_f32 v162, v100, v101
	v_cvt_pk_f16_f32 v163, v102, v103
	global_store_dwordx4 v133, v[160:163], s[6:7] sc0 sc1 nt
	v_cvt_pk_f16_f32 v164, v72, v73
	v_cvt_pk_f16_f32 v165, v74, v75
	v_cvt_pk_f16_f32 v166, v68, v69
	v_cvt_pk_f16_f32 v167, v70, v71
; __device__ __forceinline__ float row4_sum(float s) {
;     { const auto r = __builtin_amdgcn_permlane16_swap(__float_as_uint(s), __float_as_uint(s), false, false); s = __uint_as_float(r[0]) + __uint_as_float(r[1]); }
;     { const auto r = __builtin_amdgcn_permlane32_swap(__float_as_uint(s), __float_as_uint(s), false, false); s = __uint_as_float(r[0]) + __uint_as_float(r[1]); }
;     __device__ __forceinline__ void operator()(const f32x4 (&acc)[2][2][4][2], const Unit& u, int wr, int wc, int fr, int fq) const {
;     ...
;                 f32x4 v[2][2];
; #pragma unroll
;                 for (int bj = 0; bj < 2; ++bj)
; #pragma unroll
;                     for (int n = 0; n < 2; ++n) v[bj][n] = acc[ai][bj][m][n] * rs;
;                 if (sec == 4 || sec == 5) {
;                     float ss = 0.f;
; #pragma unroll
;                     for (int bj = 0; bj < 2; ++bj)
; #pragma unroll
;                         for (int n = 0; n < 2; ++n) { const f32x4 x = v[bj][n]; ss += (x[0] * x[0] + x[1] * x[1]) + (x[2] * x[2] + x[3] * x[3]); }
;                     ss = row4_sum(ss);
;                     float rn = __builtin_amdgcn_rsqf(ss * (1.0f / 64.0f) + RMS_EPS);
;                     if (sec == 4) rn *= QS;
; #pragma unroll
;                     for (int bj = 0; bj < 2; ++bj)
; #pragma unroll
;                         for (int n = 0; n < 2; ++n) v[bj][n] = v[bj][n] * rn * gain[bj][n];
;                 } else if (sec == 0) {
; #pragma unroll
;                     for (int bj = 0; bj < 2; ++bj)
; #pragma unroll
;                         for (int n = 0; n < 2; ++n) v[bj][n] = v[bj][n] * QS;
;                 } else if (sec == 3 || sec == 7) {
; #pragma unroll
;                     for (int bj = 0; bj < 2; ++bj)
; #pragma unroll
;                         for (int n = 0; n < 2; ++n)
; #pragma unroll
;                             for (int e = 0; e < 4; ++e) v[bj][n][e] = silu_f(v[bj][n][e]);
;                 }
;                 GAS f16* rowp = isqg ? QG + (size_t)dsec * QG_SEC + bl512((size_t)row, cs) : KV + (size_t)row * KVW + dsec * 512 + cs;
; #pragma unroll
;                 for (int bj = 0; bj < 2; ++bj) {
;                     u32x4 w; w.x = pkh(v[bj][0][0], v[bj][0][1]); w.y = pkh(v[bj][0][2], v[bj][0][3]); w.z = pkh(v[bj][1][0], v[bj][1][1]); w.w = pkh(v[bj][1][2], v[bj][1][3]);
;                     *(GAS u32x4*)(rowp + bjstep * bj) = w;
;                 }
	global_store_dwordx4 v133, v[164:167], s[6:7] offset:64 sc0 sc1 nt
	s_add_u32 s6, s4, 0x80000
	s_addc_u32 s7, s5, 0
	v_pk_mul_f32 v[64:65], v[64:65], v[142:143] op_sel_hi:[1,0]
	v_pk_mul_f32 v[66:67], v[66:67], v[142:143] op_sel_hi:[1,0]
	v_pk_mul_f32 v[60:61], v[60:61], v[142:143] op_sel_hi:[1,0]
	v_pk_mul_f32 v[62:63], v[62:63], v[142:143] op_sel_hi:[1,0]
	v_pk_mul_f32 v[32:33], v[32:33], v[142:143] op_sel_hi:[1,0]
	v_pk_mul_f32 v[34:35], v[34:35], v[142:143] op_sel_hi:[1,0]
	v_pk_mul_f32 v[28:29], v[28:29], v[142:143] op_sel_hi:[1,0]
	v_pk_mul_f32 v[30:31], v[30:31], v[142:143] op_sel_hi:[1,0]
	v_mul_f32_e32 v2, v64, v64
	v_mul_f32_e32 v150, v65, v65
	v_fmac_f32_e32 v2, v66, v66
	v_fmac_f32_e32 v150, v67, v67
	v_fmac_f32_e32 v2, v60, v60
	v_fmac_f32_e32 v150, v61, v61
	v_fmac_f32_e32 v2, v62, v62
	v_fmac_f32_e32 v150, v63, v63
	v_fmac_f32_e32 v2, v32, v32
	v_fmac_f32_e32 v150, v33, v33
	v_fmac_f32_e32 v2, v34, v34
	v_fmac_f32_e32 v150, v35, v35
	v_fmac_f32_e32 v2, v28, v28
	v_fmac_f32_e32 v150, v29, v29
	v_fmac_f32_e32 v2, v30, v30
	v_fmac_f32_e32 v150, v31, v31
	v_add_f32_e32 v2, v2, v150
	v_mov_b32_e32 v150, v2
	s_nop 1
	v_permlane16_swap_b32_e32 v2, v150
	v_add_f32_e32 v2, v2, v150
	v_mov_b32_e32 v150, v2
	s_nop 1
	v_permlane32_swap_b32_e32 v2, v150
	v_add_f32_e32 v2, v2, v150
	v_fmamk_f32 v2, v2, 0x3c800000, v211
	v_rsq_f32_e32 v2, v2
	s_nop 0
	v_pk_mul_f32 v[64:65], v[64:65], v[2:3] op_sel_hi:[1,0]
	v_pk_mul_f32 v[66:67], v[66:67], v[2:3] op_sel_hi:[1,0]
	v_pk_mul_f32 v[60:61], v[60:61], v[2:3] op_sel_hi:[1,0]
	v_pk_mul_f32 v[62:63], v[62:63], v[2:3] op_sel_hi:[1,0]
	v_pk_mul_f32 v[32:33], v[32:33], v[2:3] op_sel_hi:[1,0]
	v_pk_mul_f32 v[34:35], v[34:35], v[2:3] op_sel_hi:[1,0]
	v_pk_mul_f32 v[28:29], v[28:29], v[2:3] op_sel_hi:[1,0]
	v_pk_mul_f32 v[30:31], v[30:31], v[2:3] op_sel_hi:[1,0]
	v_pk_mul_f32 v[64:65], v[64:65], v[176:177]
	v_pk_mul_f32 v[66:67], v[66:67], v[178:179]
	v_pk_mul_f32 v[60:61], v[60:61], v[206:207]
	v_pk_mul_f32 v[62:63], v[62:63], v[208:209]
	v_pk_mul_f32 v[32:33], v[32:33], v[224:225]
	v_pk_mul_f32 v[34:35], v[34:35], v[226:227]
	v_pk_mul_f32 v[28:29], v[28:29], v[228:229]
	v_pk_mul_f32 v[30:31], v[30:31], v[230:231]
	v_cvt_pk_f16_f32 v152, v64, v65
	v_cvt_pk_f16_f32 v153, v66, v67
	v_cvt_pk_f16_f32 v154, v60, v61
	v_cvt_pk_f16_f32 v155, v62, v63
	global_store_dwordx4 v133, v[152:155], s[6:7] sc0 sc1 nt
	v_cvt_pk_f16_f32 v156, v32, v33
	v_cvt_pk_f16_f32 v157, v34, v35
	v_cvt_pk_f16_f32 v158, v28, v29
	v_cvt_pk_f16_f32 v159, v30, v31
	global_store_dwordx4 v133, v[156:159], s[6:7] offset:64 sc0 sc1 nt
	s_add_u32 s6, s4, 0x90000
	s_addc_u32 s7, s5, 0
	v_pk_mul_f32 v[56:57], v[56:57], v[144:145] op_sel_hi:[1,0]
	v_pk_mul_f32 v[58:59], v[58:59], v[144:145] op_sel_hi:[1,0]
	v_pk_mul_f32 v[52:53], v[52:53], v[144:145] op_sel_hi:[1,0]
	v_pk_mul_f32 v[54:55], v[54:55], v[144:145] op_sel_hi:[1,0]
	v_pk_mul_f32 v[24:25], v[24:25], v[144:145] op_sel_hi:[1,0]
	v_pk_mul_f32 v[26:27], v[26:27], v[144:145] op_sel_hi:[1,0]
	v_pk_mul_f32 v[20:21], v[20:21], v[144:145] op_sel_hi:[1,0]
	v_pk_mul_f32 v[22:23], v[22:23], v[144:145] op_sel_hi:[1,0]
	v_mul_f32_e32 v2, v56, v56
	v_mul_f32_e32 v150, v57, v57
	v_fmac_f32_e32 v2, v58, v58
	v_fmac_f32_e32 v150, v59, v59
	v_fmac_f32_e32 v2, v52, v52
	v_fmac_f32_e32 v150, v53, v53
	v_fmac_f32_e32 v2, v54, v54
	v_fmac_f32_e32 v150, v55, v55
	v_fmac_f32_e32 v2, v24, v24
	v_fmac_f32_e32 v150, v25, v25
	v_fmac_f32_e32 v2, v26, v26
	v_fmac_f32_e32 v150, v27, v27
	v_fmac_f32_e32 v2, v20, v20
	v_fmac_f32_e32 v150, v21, v21
	v_fmac_f32_e32 v2, v22, v22
	v_fmac_f32_e32 v150, v23, v23
	v_add_f32_e32 v2, v2, v150
	v_mov_b32_e32 v150, v2
	s_nop 1
	v_permlane16_swap_b32_e32 v2, v150
	v_add_f32_e32 v2, v2, v150
	v_mov_b32_e32 v150, v2
	s_nop 1
	v_permlane32_swap_b32_e32 v2, v150
	v_add_f32_e32 v2, v2, v150
	v_fmamk_f32 v2, v2, 0x3c800000, v211
	v_rsq_f32_e32 v2, v2
	s_nop 0
	v_pk_mul_f32 v[56:57], v[56:57], v[2:3] op_sel_hi:[1,0]
	v_pk_mul_f32 v[58:59], v[58:59], v[2:3] op_sel_hi:[1,0]
	v_pk_mul_f32 v[52:53], v[52:53], v[2:3] op_sel_hi:[1,0]
	v_pk_mul_f32 v[54:55], v[54:55], v[2:3] op_sel_hi:[1,0]
	v_pk_mul_f32 v[24:25], v[24:25], v[2:3] op_sel_hi:[1,0]
	v_pk_mul_f32 v[26:27], v[26:27], v[2:3] op_sel_hi:[1,0]
	v_pk_mul_f32 v[20:21], v[20:21], v[2:3] op_sel_hi:[1,0]
	v_pk_mul_f32 v[22:23], v[22:23], v[2:3] op_sel_hi:[1,0]
	v_pk_mul_f32 v[56:57], v[56:57], v[176:177]
	v_pk_mul_f32 v[58:59], v[58:59], v[178:179]
	v_pk_mul_f32 v[52:53], v[52:53], v[206:207]
	v_pk_mul_f32 v[54:55], v[54:55], v[208:209]
	v_pk_mul_f32 v[24:25], v[24:25], v[224:225]
	v_pk_mul_f32 v[26:27], v[26:27], v[226:227]
	v_pk_mul_f32 v[20:21], v[20:21], v[228:229]
	v_pk_mul_f32 v[22:23], v[22:23], v[230:231]
	v_cvt_pk_f16_f32 v160, v56, v57
	v_cvt_pk_f16_f32 v161, v58, v59
	v_cvt_pk_f16_f32 v162, v52, v53
	v_cvt_pk_f16_f32 v163, v54, v55
	global_store_dwordx4 v133, v[160:163], s[6:7] sc0 sc1 nt
	v_cvt_pk_f16_f32 v164, v24, v25
	v_cvt_pk_f16_f32 v165, v26, v27
	v_cvt_pk_f16_f32 v166, v20, v21
	v_cvt_pk_f16_f32 v167, v22, v23
; __device__ __forceinline__ float row4_sum(float s) {
;     { const auto r = __builtin_amdgcn_permlane16_swap(__float_as_uint(s), __float_as_uint(s), false, false); s = __uint_as_float(r[0]) + __uint_as_float(r[1]); }
;     { const auto r = __builtin_amdgcn_permlane32_swap(__float_as_uint(s), __float_as_uint(s), false, false); s = __uint_as_float(r[0]) + __uint_as_float(r[1]); }
;     __device__ __forceinline__ void operator()(const f32x4 (&acc)[2][2][4][2], const Unit& u, int wr, int wc, int fr, int fq) const {
;     ...
;                 f32x4 v[2][2];
; #pragma unroll
;                 for (int bj = 0; bj < 2; ++bj)
; #pragma unroll
;                     for (int n = 0; n < 2; ++n) v[bj][n] = acc[ai][bj][m][n] * rs;
;                 if (sec == 4 || sec == 5) {
;                     float ss = 0.f;
; #pragma unroll
;                     for (int bj = 0; bj < 2; ++bj)
; #pragma unroll
;                         for (int n = 0; n < 2; ++n) { const f32x4 x = v[bj][n]; ss += (x[0] * x[0] + x[1] * x[1]) + (x[2] * x[2] + x[3] * x[3]); }
;                     ss = row4_sum(ss);
;                     float rn = __builtin_amdgcn_rsqf(ss * (1.0f / 64.0f) + RMS_EPS);
;                     if (sec == 4) rn *= QS;
; #pragma unroll
;                     for (int bj = 0; bj < 2; ++bj)
; #pragma unroll
;                         for (int n = 0; n < 2; ++n) v[bj][n] = v[bj][n] * rn * gain[bj][n];
;                 } else if (sec == 0) {
; #pragma unroll
;                     for (int bj = 0; bj < 2; ++bj)
; #pragma unroll
;                         for (int n = 0; n < 2; ++n) v[bj][n] = v[bj][n] * QS;
;                 } else if (sec == 3 || sec == 7) {
; #pragma unroll
;                     for (int bj = 0; bj < 2; ++bj)
; #pragma unroll
;                         for (int n = 0; n < 2; ++n)
; #pragma unroll
;                             for (int e = 0; e < 4; ++e) v[bj][n][e] = silu_f(v[bj][n][e]);
;                 }
;                 GAS f16* rowp = isqg ? QG + (size_t)dsec * QG_SEC + bl512((size_t)row, cs) : KV + (size_t)row * KVW + dsec * 512 + cs;
; #pragma unroll
;                 for (int bj = 0; bj < 2; ++bj) {
;                     u32x4 w; w.x = pkh(v[bj][0][0], v[bj][0][1]); w.y = pkh(v[bj][0][2], v[bj][0][3]); w.z = pkh(v[bj][1][0], v[bj][1][1]); w.w = pkh(v[bj][1][2], v[bj][1][3]);
;                     *(GAS u32x4*)(rowp + bjstep * bj) = w;
;                 }
	global_store_dwordx4 v133, v[164:167], s[6:7] offset:64 sc0 sc1 nt
	s_add_u32 s6, s4, 0xa0000
	s_addc_u32 s7, s5, 0
	v_pk_mul_f32 v[48:49], v[48:49], v[146:147] op_sel_hi:[1,0]
	v_pk_mul_f32 v[50:51], v[50:51], v[146:147] op_sel_hi:[1,0]
	v_pk_mul_f32 v[44:45], v[44:45], v[146:147] op_sel_hi:[1,0]
	v_pk_mul_f32 v[46:47], v[46:47], v[146:147] op_sel_hi:[1,0]
	v_pk_mul_f32 v[16:17], v[16:17], v[146:147] op_sel_hi:[1,0]
	v_pk_mul_f32 v[18:19], v[18:19], v[146:147] op_sel_hi:[1,0]
	v_pk_mul_f32 v[12:13], v[12:13], v[146:147] op_sel_hi:[1,0]
	v_pk_mul_f32 v[14:15], v[14:15], v[146:147] op_sel_hi:[1,0]
	v_mul_f32_e32 v2, v48, v48
	v_mul_f32_e32 v150, v49, v49
	v_fmac_f32_e32 v2, v50, v50
	v_fmac_f32_e32 v150, v51, v51
	v_fmac_f32_e32 v2, v44, v44
	v_fmac_f32_e32 v150, v45, v45
	v_fmac_f32_e32 v2, v46, v46
	v_fmac_f32_e32 v150, v47, v47
	v_fmac_f32_e32 v2, v16, v16
	v_fmac_f32_e32 v150, v17, v17
	v_fmac_f32_e32 v2, v18, v18
	v_fmac_f32_e32 v150, v19, v19
	v_fmac_f32_e32 v2, v12, v12
	v_fmac_f32_e32 v150, v13, v13
	v_fmac_f32_e32 v2, v14, v14
	v_fmac_f32_e32 v150, v15, v15
	v_add_f32_e32 v2, v2, v150
	v_mov_b32_e32 v150, v2
	s_nop 1
	v_permlane16_swap_b32_e32 v2, v150
	v_add_f32_e32 v2, v2, v150
	v_mov_b32_e32 v150, v2
	s_nop 1
	v_permlane32_swap_b32_e32 v2, v150
	v_add_f32_e32 v2, v2, v150
	v_fmamk_f32 v2, v2, 0x3c800000, v211
	v_rsq_f32_e32 v2, v2
	s_nop 0
	v_pk_mul_f32 v[48:49], v[48:49], v[2:3] op_sel_hi:[1,0]
	v_pk_mul_f32 v[50:51], v[50:51], v[2:3] op_sel_hi:[1,0]
	v_pk_mul_f32 v[44:45], v[44:45], v[2:3] op_sel_hi:[1,0]
	v_pk_mul_f32 v[46:47], v[46:47], v[2:3] op_sel_hi:[1,0]
	v_pk_mul_f32 v[16:17], v[16:17], v[2:3] op_sel_hi:[1,0]
	v_pk_mul_f32 v[18:19], v[18:19], v[2:3] op_sel_hi:[1,0]
	v_pk_mul_f32 v[12:13], v[12:13], v[2:3] op_sel_hi:[1,0]
	v_pk_mul_f32 v[14:15], v[14:15], v[2:3] op_sel_hi:[1,0]
	v_pk_mul_f32 v[48:49], v[48:49], v[176:177]
	v_pk_mul_f32 v[50:51], v[50:51], v[178:179]
	v_pk_mul_f32 v[44:45], v[44:45], v[206:207]
	v_pk_mul_f32 v[46:47], v[46:47], v[208:209]
	v_pk_mul_f32 v[16:17], v[16:17], v[224:225]
	v_pk_mul_f32 v[18:19], v[18:19], v[226:227]
	v_pk_mul_f32 v[12:13], v[12:13], v[228:229]
	v_pk_mul_f32 v[14:15], v[14:15], v[230:231]
	v_cvt_pk_f16_f32 v152, v48, v49
	v_cvt_pk_f16_f32 v153, v50, v51
	v_cvt_pk_f16_f32 v154, v44, v45
	v_cvt_pk_f16_f32 v155, v46, v47
	global_store_dwordx4 v133, v[152:155], s[6:7] sc0 sc1 nt
	v_cvt_pk_f16_f32 v156, v16, v17
	v_cvt_pk_f16_f32 v157, v18, v19
	v_cvt_pk_f16_f32 v158, v12, v13
	v_cvt_pk_f16_f32 v159, v14, v15
	global_store_dwordx4 v133, v[156:159], s[6:7] offset:64 sc0 sc1 nt
	s_add_u32 s6, s4, 0xb0000
	s_addc_u32 s7, s5, 0
	v_pk_mul_f32 v[40:41], v[40:41], v[148:149] op_sel_hi:[1,0]
	v_pk_mul_f32 v[42:43], v[42:43], v[148:149] op_sel_hi:[1,0]
	v_pk_mul_f32 v[36:37], v[36:37], v[148:149] op_sel_hi:[1,0]
	v_pk_mul_f32 v[38:39], v[38:39], v[148:149] op_sel_hi:[1,0]
	v_pk_mul_f32 v[8:9], v[8:9], v[148:149] op_sel_hi:[1,0]
	v_pk_mul_f32 v[10:11], v[10:11], v[148:149] op_sel_hi:[1,0]
	v_pk_mul_f32 v[4:5], v[4:5], v[148:149] op_sel_hi:[1,0]
	v_pk_mul_f32 v[6:7], v[6:7], v[148:149] op_sel_hi:[1,0]
	v_mul_f32_e32 v2, v40, v40
	v_mul_f32_e32 v150, v41, v41
	v_fmac_f32_e32 v2, v42, v42
	v_fmac_f32_e32 v150, v43, v43
	v_fmac_f32_e32 v2, v36, v36
	v_fmac_f32_e32 v150, v37, v37
	v_fmac_f32_e32 v2, v38, v38
	v_fmac_f32_e32 v150, v39, v39
	v_fmac_f32_e32 v2, v8, v8
	v_fmac_f32_e32 v150, v9, v9
	v_fmac_f32_e32 v2, v10, v10
	v_fmac_f32_e32 v150, v11, v11
	v_fmac_f32_e32 v2, v4, v4
	v_fmac_f32_e32 v150, v5, v5
	v_fmac_f32_e32 v2, v6, v6
	v_fmac_f32_e32 v150, v7, v7
	v_add_f32_e32 v2, v2, v150
	v_mov_b32_e32 v150, v2
	s_nop 1
	v_permlane16_swap_b32_e32 v2, v150
	v_add_f32_e32 v2, v2, v150
	v_mov_b32_e32 v150, v2
	s_nop 1
	v_permlane32_swap_b32_e32 v2, v150
	v_add_f32_e32 v2, v2, v150
	v_fmamk_f32 v2, v2, 0x3c800000, v211
	v_rsq_f32_e32 v2, v2
	s_nop 0
	v_pk_mul_f32 v[40:41], v[40:41], v[2:3] op_sel_hi:[1,0]
	v_pk_mul_f32 v[42:43], v[42:43], v[2:3] op_sel_hi:[1,0]
	v_pk_mul_f32 v[36:37], v[36:37], v[2:3] op_sel_hi:[1,0]
	v_pk_mul_f32 v[38:39], v[38:39], v[2:3] op_sel_hi:[1,0]
	v_pk_mul_f32 v[8:9], v[8:9], v[2:3] op_sel_hi:[1,0]
	v_pk_mul_f32 v[10:11], v[10:11], v[2:3] op_sel_hi:[1,0]
	v_pk_mul_f32 v[4:5], v[4:5], v[2:3] op_sel_hi:[1,0]
	v_pk_mul_f32 v[6:7], v[6:7], v[2:3] op_sel_hi:[1,0]
	v_pk_mul_f32 v[40:41], v[40:41], v[176:177]
	v_pk_mul_f32 v[42:43], v[42:43], v[178:179]
	v_pk_mul_f32 v[36:37], v[36:37], v[206:207]
	v_pk_mul_f32 v[38:39], v[38:39], v[208:209]
	v_pk_mul_f32 v[8:9], v[8:9], v[224:225]
	v_pk_mul_f32 v[10:11], v[10:11], v[226:227]
	v_pk_mul_f32 v[4:5], v[4:5], v[228:229]
	v_pk_mul_f32 v[6:7], v[6:7], v[230:231]
	v_cvt_pk_f16_f32 v160, v40, v41
	v_cvt_pk_f16_f32 v161, v42, v43
	v_cvt_pk_f16_f32 v162, v36, v37
	v_cvt_pk_f16_f32 v163, v38, v39
	global_store_dwordx4 v133, v[160:163], s[6:7] sc0 sc1 nt
	v_cvt_pk_f16_f32 v164, v8, v9
	v_cvt_pk_f16_f32 v165, v10, v11
	v_cvt_pk_f16_f32 v166, v4, v5
	v_cvt_pk_f16_f32 v167, v6, v7
	global_store_dwordx4 v133, v[164:167], s[6:7] offset:64 sc0 sc1 nt
	s_branch .Lepi_done_g1
